# GEMM K-loops (G1, G3, UP, G6a): loop counter/pointer SALU block rotated ahead of the closing barrier (back-edge rotation)
# baseline (speedup 1.0000x reference)
; #define PG8_STAGE(bufoff, gbase, voff) do { _Pragma("unroll") for (int _i = 0; _i < 2; ++_i) \
;         __builtin_amdgcn_global_load_lds((const unsigned*)((const char*)(gbase) + (voff)[_i]), (PG8_LAS unsigned*)(lds + (bufoff) + ldsw + _i * 8192), 16, 0, 0); } while (0)
; #define PG8_LDA(dst, b, h) do { _Pragma("unroll") for (int m = 0; m < 4; ++m) _Pragma("unroll") for (int k = 0; k < 2; ++k) dst[m][k] = *(const PG8_LAS bf16x8*)(lds + PG8_SA(b, h) + aoff + m * 2048 + k * 1024); } while (0)
; #define PG8_LDB(dst, b, h) do { _Pragma("unroll") for (int n = 0; n < 2; ++n) _Pragma("unroll") for (int k = 0; k < 2; ++k) dst[n][k] = *(const PG8_LAS bf16x8*)(lds + PG8_SB(b, h) + boff + n * 2048 + k * 1024); } while (0)
; #define PG8_MMA(ai, bj, At, Bt) do { __builtin_amdgcn_s_setprio(1); _Pragma("unroll") for (int m = 0; m < 4; ++m) _Pragma("unroll") for (int n = 0; n < 2; ++n) _Pragma("unroll") for (int k = 0; k < 2; ++k) \
;         acc[ai][bj][m][n] = __builtin_amdgcn_mfma_f32_16x16x32_bf16(Bt[n][k], At[m][k], acc[ai][bj][m][n], 0, 0, 0); __builtin_amdgcn_s_setprio(0); } while (0)
; #define PG8_WAIT_V(n) asm volatile("s_waitcnt vmcnt(" #n ")" ::: "memory")
; #define PG8_WAIT_L(n) asm volatile("s_waitcnt lgkmcnt(" #n ")" ::: "memory")
; #define PG8_BAR __builtin_amdgcn_s_barrier()
; #define PG8_SCHED __builtin_amdgcn_sched_barrier(0)
; template <class Epi, class Sched, bool ALIGN_EPI = false, bool SP2 = false>
; __device__ __forceinline__ void gemm_phase(PG8_LAS unsigned char* lds, const Gemm g, const Sched& S, const Epi& E, const int tid_in) {
;     ...
;             const bool last = (t == nt - 2);
;             const char* a1 = cA + (size_t)(t + 1) * kstep;
;             const char* a2 = last ? nA : cA + (size_t)(t + 2) * kstep; const char* b2 = last ? nB : cB + (size_t)(t + 2) * kstep;
;             const char* a3 = a2 + kstep; const char* b3 = b2 + kstep;
;             if (last && has_next) S.a_ready(nxt);
;             if constexpr (SP2) {
;             PG8_LDB(B0, 0, 0); PG8_LDB(B1, 0, 1); PG8_SCHED; PG8_LDA(At, 0, 0); PG8_STAGE(PG8_SA(1, 1), a1 + hstepA, voffA);
;             PG8_WAIT_V(8); PG8_WAIT_L(0); PG8_BAR; PG8_MMA(0, 0, At, B0); PG8_MMA(0, 1, At, B1); PG8_BAR; PG8_SCHED;
;             PG8_LDA(At, 0, 1); PG8_STAGE(PG8_SB(0, 0), b2, voffB); PG8_STAGE(PG8_SB(0, 1), b2 + hstepB, voffB); PG8_STAGE(PG8_SA(0, 0), a2, voffA);
.LBB0_286:
	s_add_u32 s22, s20, 0xfffc0080
	s_addc_u32 s23, s21, -1
	s_add_i32 s47, 0, 0x10000
	s_cmp_eq_u32 s46, 12
	s_cselect_b32 s25, s15, s23
	s_cselect_b32 s24, s42, s22
	v_add_u32_e32 v142, s47, v143
	s_cselect_b32 s23, s13, s45
	s_cselect_b32 s22, s43, s44
	s_add_i32 s52, 0, 0x14000
	ds_read_b128 v[146:149], v142
	ds_read_b128 v[150:153], v142 offset:1024
	ds_read_b128 v[154:157], v142 offset:2048
	ds_read_b128 v[158:161], v142 offset:3072
	v_add_u32_e32 v142, s52, v143
	ds_read_b128 v[162:165], v142
	ds_read_b128 v[166:169], v142 offset:1024
	ds_read_b128 v[170:173], v142 offset:2048
	ds_read_b128 v[174:177], v142 offset:3072
	v_lshl_add_u64 v[194:195], s[20:21], 0, v[138:139]
	s_add_i32 m0, s29, 0xc000
	ds_read_b128 v[178:181], v145
	ds_read_b128 v[182:185], v145 offset:1024
	ds_read_b128 v[186:189], v145 offset:2048
	ds_read_b128 v[190:193], v145 offset:3072
	ds_read_b128 v[200:203], v145 offset:4096
	ds_read_b128 v[204:207], v145 offset:5120
	ds_read_b128 v[208:211], v145 offset:6144
	ds_read_b128 v[212:215], v145 offset:7168
	global_load_lds_dwordx4 v[194:195], off
	v_lshl_add_u64 v[194:195], s[20:21], 0, v[140:141]
	s_add_i32 m0, s29, 0xe000
	s_nop 0
	global_load_lds_dwordx4 v[194:195], off
	s_waitcnt vmcnt(8)
	s_waitcnt lgkmcnt(0)
	s_barrier
	s_setprio 1
	s_waitcnt lgkmcnt(0)
	v_mfma_f32_16x16x32_bf16 v[128:131], v[146:149], v[178:181], v[128:131]
	v_mfma_f32_16x16x32_bf16 v[124:127], v[154:157], v[178:181], v[124:127]
	v_mfma_f32_16x16x32_bf16 v[112:115], v[146:149], v[186:189], v[112:115]
	v_mfma_f32_16x16x32_bf16 v[108:111], v[154:157], v[186:189], v[108:111]
	v_mfma_f32_16x16x32_bf16 v[92:95], v[146:149], v[200:203], v[92:95]
	v_mfma_f32_16x16x32_bf16 v[88:91], v[154:157], v[200:203], v[88:91]
	v_mfma_f32_16x16x32_bf16 v[84:87], v[146:149], v[208:211], v[84:87]
	v_mfma_f32_16x16x32_bf16 v[76:79], v[154:157], v[208:211], v[76:79]
	v_mfma_f32_16x16x32_bf16 v[128:131], v[150:153], v[182:185], v[128:131]
	v_mfma_f32_16x16x32_bf16 v[124:127], v[158:161], v[182:185], v[124:127]
	v_mfma_f32_16x16x32_bf16 v[112:115], v[150:153], v[190:193], v[112:115]
	v_mfma_f32_16x16x32_bf16 v[108:111], v[158:161], v[190:193], v[108:111]
	v_mfma_f32_16x16x32_bf16 v[92:95], v[150:153], v[204:207], v[92:95]
	v_mfma_f32_16x16x32_bf16 v[88:91], v[158:161], v[204:207], v[88:91]
	v_mfma_f32_16x16x32_bf16 v[84:87], v[150:153], v[212:215], v[84:87]
	v_mfma_f32_16x16x32_bf16 v[76:79], v[158:161], v[212:215], v[76:79]
	s_setprio 0
	s_setprio 1
	v_mfma_f32_16x16x32_bf16 v[120:123], v[162:165], v[178:181], v[120:123]
	v_mfma_f32_16x16x32_bf16 v[116:119], v[170:173], v[178:181], v[116:119]
	v_mfma_f32_16x16x32_bf16 v[104:107], v[162:165], v[186:189], v[104:107]
	v_mfma_f32_16x16x32_bf16 v[100:103], v[170:173], v[186:189], v[100:103]
	v_mfma_f32_16x16x32_bf16 v[80:83], v[162:165], v[200:203], v[80:83]
	v_mfma_f32_16x16x32_bf16 v[72:75], v[170:173], v[200:203], v[72:75]
	v_mfma_f32_16x16x32_bf16 v[68:71], v[162:165], v[208:211], v[68:71]
	v_mfma_f32_16x16x32_bf16 v[64:67], v[170:173], v[208:211], v[64:67]
	v_mfma_f32_16x16x32_bf16 v[120:123], v[166:169], v[182:185], v[120:123]
	v_mfma_f32_16x16x32_bf16 v[116:119], v[174:177], v[182:185], v[116:119]
	v_mfma_f32_16x16x32_bf16 v[104:107], v[166:169], v[190:193], v[104:107]
	v_mfma_f32_16x16x32_bf16 v[100:103], v[174:177], v[190:193], v[100:103]
	v_mfma_f32_16x16x32_bf16 v[80:83], v[166:169], v[204:207], v[80:83]
	v_mfma_f32_16x16x32_bf16 v[72:75], v[174:177], v[204:207], v[72:75]
	v_mfma_f32_16x16x32_bf16 v[68:71], v[166:169], v[212:215], v[68:71]
	v_mfma_f32_16x16x32_bf16 v[64:67], v[174:177], v[212:215], v[64:67]
	s_setprio 0
	s_barrier
	s_add_i32 s47, s47, s28
	v_lshl_add_u64 v[194:195], s[22:23], 0, v[134:135]
	s_mov_b32 m0, s47
	ds_read_b128 v[178:181], v145 offset:16384
	ds_read_b128 v[182:185], v145 offset:17408
	ds_read_b128 v[186:189], v145 offset:18432
	ds_read_b128 v[190:193], v145 offset:19456
	ds_read_b128 v[200:203], v145 offset:20480
	ds_read_b128 v[204:207], v145 offset:21504
	ds_read_b128 v[208:211], v145 offset:22528
	ds_read_b128 v[212:215], v145 offset:23552
	global_load_lds_dwordx4 v[194:195], off
	s_add_i32 m0, s47, 0x2000
	s_add_u32 s48, s22, 0x40000
	v_lshl_add_u64 v[196:197], s[22:23], 0, v[96:97]
	s_addc_u32 s49, s23, 0
	s_add_i32 s47, s52, s28
	global_load_lds_dwordx4 v[196:197], off
	v_lshl_add_u64 v[216:217], s[48:49], 0, v[134:135]
	s_mov_b32 m0, s47
	v_lshl_add_u64 v[218:219], s[24:25], 0, v[132:133]
	global_load_lds_dwordx4 v[216:217], off
	v_lshl_add_u64 v[216:217], s[48:49], 0, v[96:97]
	s_add_i32 m0, s47, 0x2000
	s_nop 0
	global_load_lds_dwordx4 v[216:217], off
	v_lshl_add_u64 v[216:217], s[24:25], 0, v[136:137]
	s_mov_b32 m0, s29
	s_nop 0
	global_load_lds_dwordx4 v[216:217], off
	s_mov_b32 m0, s30
	s_nop 0
	global_load_lds_dwordx4 v[218:219], off
	s_waitcnt vmcnt(8)
	s_waitcnt lgkmcnt(0)
	s_barrier
; #define PG8_STAGE(bufoff, gbase, voff) do { _Pragma("unroll") for (int _i = 0; _i < 2; ++_i) \
;         __builtin_amdgcn_global_load_lds((const unsigned*)((const char*)(gbase) + (voff)[_i]), (PG8_LAS unsigned*)(lds + (bufoff) + ldsw + _i * 8192), 16, 0, 0); } while (0)
; #define PG8_LDA(dst, b, h) do { _Pragma("unroll") for (int m = 0; m < 4; ++m) _Pragma("unroll") for (int k = 0; k < 2; ++k) dst[m][k] = *(const PG8_LAS bf16x8*)(lds + PG8_SA(b, h) + aoff + m * 2048 + k * 1024); } while (0)
; #define PG8_LDB(dst, b, h) do { _Pragma("unroll") for (int n = 0; n < 2; ++n) _Pragma("unroll") for (int k = 0; k < 2; ++k) dst[n][k] = *(const PG8_LAS bf16x8*)(lds + PG8_SB(b, h) + boff + n * 2048 + k * 1024); } while (0)
; #define PG8_MMA(ai, bj, At, Bt) do { __builtin_amdgcn_s_setprio(1); _Pragma("unroll") for (int m = 0; m < 4; ++m) _Pragma("unroll") for (int n = 0; n < 2; ++n) _Pragma("unroll") for (int k = 0; k < 2; ++k) \
;         acc[ai][bj][m][n] = __builtin_amdgcn_mfma_f32_16x16x32_bf16(Bt[n][k], At[m][k], acc[ai][bj][m][n], 0, 0, 0); __builtin_amdgcn_s_setprio(0); } while (0)
; #define PG8_WAIT_V(n) asm volatile("s_waitcnt vmcnt(" #n ")" ::: "memory")
; #define PG8_WAIT_L(n) asm volatile("s_waitcnt lgkmcnt(" #n ")" ::: "memory")
; #define PG8_BAR __builtin_amdgcn_s_barrier()
; #define PG8_SCHED __builtin_amdgcn_sched_barrier(0)
; template <class Epi, class Sched, bool ALIGN_EPI = false, bool SP2 = false>
; __device__ __forceinline__ void gemm_phase(PG8_LAS unsigned char* lds, const Gemm g, const Sched& S, const Epi& E, const int tid_in) {
;     ...
;             PG8_WAIT_V(8); PG8_WAIT_L(0); PG8_BAR; PG8_MMA(1, 0, At, B0); PG8_MMA(1, 1, At, B1); PG8_BAR; PG8_SCHED;
;             PG8_LDB(B0, 1, 0); PG8_LDB(B1, 1, 1); PG8_SCHED; PG8_LDA(At, 1, 0); PG8_STAGE(PG8_SA(0, 1), a2 + hstepA, voffA);
;             PG8_WAIT_V(8); PG8_WAIT_L(0); PG8_BAR; PG8_MMA(0, 0, At, B0); PG8_MMA(0, 1, At, B1); PG8_BAR; PG8_SCHED;
	s_setprio 1
	s_waitcnt lgkmcnt(0)
	v_mfma_f32_16x16x32_bf16 v[60:63], v[146:149], v[178:181], v[60:63]
	v_mfma_f32_16x16x32_bf16 v[56:59], v[154:157], v[178:181], v[56:59]
	v_mfma_f32_16x16x32_bf16 v[52:55], v[146:149], v[186:189], v[52:55]
	v_mfma_f32_16x16x32_bf16 v[44:47], v[154:157], v[186:189], v[44:47]
	v_mfma_f32_16x16x32_bf16 v[36:39], v[146:149], v[200:203], v[36:39]
	v_mfma_f32_16x16x32_bf16 v[28:31], v[154:157], v[200:203], v[28:31]
	v_mfma_f32_16x16x32_bf16 v[20:23], v[146:149], v[208:211], v[20:23]
	v_mfma_f32_16x16x32_bf16 v[12:15], v[154:157], v[208:211], v[12:15]
	v_mfma_f32_16x16x32_bf16 v[60:63], v[150:153], v[182:185], v[60:63]
	v_mfma_f32_16x16x32_bf16 v[56:59], v[158:161], v[182:185], v[56:59]
	v_mfma_f32_16x16x32_bf16 v[52:55], v[150:153], v[190:193], v[52:55]
	v_mfma_f32_16x16x32_bf16 v[44:47], v[158:161], v[190:193], v[44:47]
	v_mfma_f32_16x16x32_bf16 v[36:39], v[150:153], v[204:207], v[36:39]
	v_mfma_f32_16x16x32_bf16 v[28:31], v[158:161], v[204:207], v[28:31]
	v_mfma_f32_16x16x32_bf16 v[20:23], v[150:153], v[212:215], v[20:23]
	v_mfma_f32_16x16x32_bf16 v[12:15], v[158:161], v[212:215], v[12:15]
	s_setprio 0
	s_setprio 1
	v_mfma_f32_16x16x32_bf16 v[48:51], v[162:165], v[178:181], v[48:51]
	v_mfma_f32_16x16x32_bf16 v[40:43], v[170:173], v[178:181], v[40:43]
	v_mfma_f32_16x16x32_bf16 v[32:35], v[162:165], v[186:189], v[32:35]
	v_mfma_f32_16x16x32_bf16 v[24:27], v[170:173], v[186:189], v[24:27]
	v_mfma_f32_16x16x32_bf16 v[16:19], v[162:165], v[200:203], v[16:19]
	v_mfma_f32_16x16x32_bf16 v[8:11], v[170:173], v[200:203], v[8:11]
	v_mfma_f32_16x16x32_bf16 v[4:7], v[162:165], v[208:211], v[4:7]
	v_mfma_f32_16x16x32_bf16 v[0:3], v[170:173], v[208:211], v[0:3]
	v_mfma_f32_16x16x32_bf16 v[48:51], v[166:169], v[182:185], v[48:51]
	v_mfma_f32_16x16x32_bf16 v[40:43], v[174:177], v[182:185], v[40:43]
	v_mfma_f32_16x16x32_bf16 v[32:35], v[166:169], v[190:193], v[32:35]
	v_mfma_f32_16x16x32_bf16 v[24:27], v[174:177], v[190:193], v[24:27]
	v_mfma_f32_16x16x32_bf16 v[16:19], v[166:169], v[204:207], v[16:19]
	v_mfma_f32_16x16x32_bf16 v[8:11], v[174:177], v[204:207], v[8:11]
	v_mfma_f32_16x16x32_bf16 v[4:7], v[166:169], v[212:215], v[4:7]
	v_mfma_f32_16x16x32_bf16 v[0:3], v[174:177], v[212:215], v[0:3]
	s_setprio 0
	s_barrier
	s_add_i32 s47, 0, 0x18000
	v_add_u32_e32 v142, s47, v143
	s_add_i32 s48, 0, 0x1c000
	ds_read_b128 v[146:149], v142
	ds_read_b128 v[150:153], v142 offset:1024
	ds_read_b128 v[154:157], v142 offset:2048
	ds_read_b128 v[158:161], v142 offset:3072
	v_add_u32_e32 v142, s48, v143
	ds_read_b128 v[162:165], v142
	ds_read_b128 v[166:169], v142 offset:1024
	ds_read_b128 v[170:173], v142 offset:2048
	ds_read_b128 v[174:177], v142 offset:3072
	s_add_u32 s24, s24, 0x40000
	s_addc_u32 s25, s25, 0
	s_mov_b32 m0, s31
	v_lshl_add_u64 v[220:221], s[24:25], 0, v[136:137]
	ds_read_b128 v[178:181], v145 offset:32768
	ds_read_b128 v[182:185], v145 offset:33792
	ds_read_b128 v[186:189], v145 offset:34816
	ds_read_b128 v[190:193], v145 offset:35840
	ds_read_b128 v[200:203], v145 offset:36864
	ds_read_b128 v[204:207], v145 offset:37888
	ds_read_b128 v[208:211], v145 offset:38912
	ds_read_b128 v[212:215], v145 offset:39936
	global_load_lds_dwordx4 v[220:221], off
	v_lshl_add_u64 v[220:221], s[24:25], 0, v[132:133]
	s_mov_b32 m0, s34
	s_nop 0
	global_load_lds_dwordx4 v[220:221], off
	s_waitcnt vmcnt(8)
	s_waitcnt lgkmcnt(0)
	s_barrier
	s_setprio 1
	s_waitcnt lgkmcnt(0)
	v_mfma_f32_16x16x32_bf16 v[128:131], v[146:149], v[178:181], v[128:131]
	v_mfma_f32_16x16x32_bf16 v[124:127], v[154:157], v[178:181], v[124:127]
	v_mfma_f32_16x16x32_bf16 v[112:115], v[146:149], v[186:189], v[112:115]
	v_mfma_f32_16x16x32_bf16 v[108:111], v[154:157], v[186:189], v[108:111]
	v_mfma_f32_16x16x32_bf16 v[92:95], v[146:149], v[200:203], v[92:95]
	v_mfma_f32_16x16x32_bf16 v[88:91], v[154:157], v[200:203], v[88:91]
	v_mfma_f32_16x16x32_bf16 v[84:87], v[146:149], v[208:211], v[84:87]
	v_mfma_f32_16x16x32_bf16 v[76:79], v[154:157], v[208:211], v[76:79]
	v_mfma_f32_16x16x32_bf16 v[128:131], v[150:153], v[182:185], v[128:131]
	v_mfma_f32_16x16x32_bf16 v[124:127], v[158:161], v[182:185], v[124:127]
	v_mfma_f32_16x16x32_bf16 v[112:115], v[150:153], v[190:193], v[112:115]
	v_mfma_f32_16x16x32_bf16 v[108:111], v[158:161], v[190:193], v[108:111]
	v_mfma_f32_16x16x32_bf16 v[92:95], v[150:153], v[204:207], v[92:95]
	v_mfma_f32_16x16x32_bf16 v[88:91], v[158:161], v[204:207], v[88:91]
	v_mfma_f32_16x16x32_bf16 v[84:87], v[150:153], v[212:215], v[84:87]
	v_mfma_f32_16x16x32_bf16 v[76:79], v[158:161], v[212:215], v[76:79]
	s_setprio 0
	s_setprio 1
	v_mfma_f32_16x16x32_bf16 v[120:123], v[162:165], v[178:181], v[120:123]
	v_mfma_f32_16x16x32_bf16 v[116:119], v[170:173], v[178:181], v[116:119]
	v_mfma_f32_16x16x32_bf16 v[104:107], v[162:165], v[186:189], v[104:107]
	v_mfma_f32_16x16x32_bf16 v[100:103], v[170:173], v[186:189], v[100:103]
	v_mfma_f32_16x16x32_bf16 v[80:83], v[162:165], v[200:203], v[80:83]
	v_mfma_f32_16x16x32_bf16 v[72:75], v[170:173], v[200:203], v[72:75]
	v_mfma_f32_16x16x32_bf16 v[68:71], v[162:165], v[208:211], v[68:71]
	v_mfma_f32_16x16x32_bf16 v[64:67], v[170:173], v[208:211], v[64:67]
	v_mfma_f32_16x16x32_bf16 v[120:123], v[166:169], v[182:185], v[120:123]
	v_mfma_f32_16x16x32_bf16 v[116:119], v[174:177], v[182:185], v[116:119]
	v_mfma_f32_16x16x32_bf16 v[104:107], v[166:169], v[190:193], v[104:107]
	v_mfma_f32_16x16x32_bf16 v[100:103], v[174:177], v[190:193], v[100:103]
	v_mfma_f32_16x16x32_bf16 v[80:83], v[166:169], v[204:207], v[80:83]
	v_mfma_f32_16x16x32_bf16 v[72:75], v[174:177], v[204:207], v[72:75]
	v_mfma_f32_16x16x32_bf16 v[68:71], v[166:169], v[212:215], v[68:71]
	v_mfma_f32_16x16x32_bf16 v[64:67], v[174:177], v[212:215], v[64:67]
	s_setprio 0
	s_barrier
; #define PG8_STAGE(bufoff, gbase, voff) do { _Pragma("unroll") for (int _i = 0; _i < 2; ++_i) \
;         __builtin_amdgcn_global_load_lds((const unsigned*)((const char*)(gbase) + (voff)[_i]), (PG8_LAS unsigned*)(lds + (bufoff) + ldsw + _i * 8192), 16, 0, 0); } while (0)
; #define PG8_LDA(dst, b, h) do { _Pragma("unroll") for (int m = 0; m < 4; ++m) _Pragma("unroll") for (int k = 0; k < 2; ++k) dst[m][k] = *(const PG8_LAS bf16x8*)(lds + PG8_SA(b, h) + aoff + m * 2048 + k * 1024); } while (0)
; #define PG8_MMA(ai, bj, At, Bt) do { __builtin_amdgcn_s_setprio(1); _Pragma("unroll") for (int m = 0; m < 4; ++m) _Pragma("unroll") for (int n = 0; n < 2; ++n) _Pragma("unroll") for (int k = 0; k < 2; ++k) \
;         acc[ai][bj][m][n] = __builtin_amdgcn_mfma_f32_16x16x32_bf16(Bt[n][k], At[m][k], acc[ai][bj][m][n], 0, 0, 0); __builtin_amdgcn_s_setprio(0); } while (0)
; #define PG8_WAIT_V(n) asm volatile("s_waitcnt vmcnt(" #n ")" ::: "memory")
; #define PG8_WAIT_L(n) asm volatile("s_waitcnt lgkmcnt(" #n ")" ::: "memory")
; #define PG8_BAR __builtin_amdgcn_s_barrier()
; #define PG8_SCHED __builtin_amdgcn_sched_barrier(0)
; template <class Epi, class Sched, bool ALIGN_EPI = false, bool SP2 = false>
; __device__ __forceinline__ void gemm_phase(PG8_LAS unsigned char* lds, const Gemm g, const Sched& S, const Epi& E, const int tid_in) {
;     ...
;             PG8_LDA(At, 1, 1); PG8_STAGE(PG8_SB(1, 0), b3, voffB); PG8_STAGE(PG8_SB(1, 1), b3 + hstepB, voffB); PG8_STAGE(PG8_SA(1, 0), a3, voffA);
;             PG8_WAIT_V(8); PG8_WAIT_L(0); PG8_BAR; PG8_MMA(1, 0, At, B0); PG8_MMA(1, 1, At, B1); PG8_BAR; PG8_SCHED;
;     ...
;         if constexpr (ALIGN_EPI) { if (wr == 0) PG8_BAR; }
	s_add_i32 s24, s47, s28
	v_lshl_add_u64 v[194:195], v[194:195], 0, s[50:51]
	s_mov_b32 m0, s24
	ds_read_b128 v[178:181], v145 offset:49152
	ds_read_b128 v[182:185], v145 offset:50176
	ds_read_b128 v[186:189], v145 offset:51200
	ds_read_b128 v[190:193], v145 offset:52224
	ds_read_b128 v[200:203], v145 offset:53248
	ds_read_b128 v[204:207], v145 offset:54272
	ds_read_b128 v[208:211], v145 offset:55296
	ds_read_b128 v[212:215], v145 offset:56320
	global_load_lds_dwordx4 v[194:195], off
	s_add_i32 m0, s24, 0x2000
	s_add_u32 s22, s22, 0x40080
	v_lshl_add_u64 v[194:195], v[196:197], 0, s[50:51]
	s_addc_u32 s23, s23, 0
	s_add_i32 s24, s48, s28
	global_load_lds_dwordx4 v[194:195], off
	v_lshl_add_u64 v[194:195], s[22:23], 0, v[134:135]
	s_mov_b32 m0, s24
	s_nop 0
	global_load_lds_dwordx4 v[194:195], off
	v_lshl_add_u64 v[194:195], s[22:23], 0, v[96:97]
	s_add_i32 m0, s24, 0x2000
	s_nop 0
	global_load_lds_dwordx4 v[194:195], off
	v_lshl_add_u64 v[194:195], v[216:217], 0, s[50:51]
	s_mov_b32 m0, s37
	s_nop 0
	global_load_lds_dwordx4 v[194:195], off
	v_lshl_add_u64 v[194:195], v[218:219], 0, s[50:51]
	s_mov_b32 m0, s38
	s_nop 0
	global_load_lds_dwordx4 v[194:195], off
	s_waitcnt vmcnt(8)
	s_waitcnt lgkmcnt(0)
	s_barrier
	s_setprio 1
	s_waitcnt lgkmcnt(0)
	v_mfma_f32_16x16x32_bf16 v[60:63], v[146:149], v[178:181], v[60:63]
	v_mfma_f32_16x16x32_bf16 v[56:59], v[154:157], v[178:181], v[56:59]
	v_mfma_f32_16x16x32_bf16 v[52:55], v[146:149], v[186:189], v[52:55]
	v_mfma_f32_16x16x32_bf16 v[44:47], v[154:157], v[186:189], v[44:47]
	v_mfma_f32_16x16x32_bf16 v[36:39], v[146:149], v[200:203], v[36:39]
	v_mfma_f32_16x16x32_bf16 v[28:31], v[154:157], v[200:203], v[28:31]
	v_mfma_f32_16x16x32_bf16 v[20:23], v[146:149], v[208:211], v[20:23]
	v_mfma_f32_16x16x32_bf16 v[12:15], v[154:157], v[208:211], v[12:15]
	v_mfma_f32_16x16x32_bf16 v[60:63], v[150:153], v[182:185], v[60:63]
	v_mfma_f32_16x16x32_bf16 v[56:59], v[158:161], v[182:185], v[56:59]
	v_mfma_f32_16x16x32_bf16 v[52:55], v[150:153], v[190:193], v[52:55]
	v_mfma_f32_16x16x32_bf16 v[44:47], v[158:161], v[190:193], v[44:47]
	v_mfma_f32_16x16x32_bf16 v[36:39], v[150:153], v[204:207], v[36:39]
	v_mfma_f32_16x16x32_bf16 v[28:31], v[158:161], v[204:207], v[28:31]
	v_mfma_f32_16x16x32_bf16 v[20:23], v[150:153], v[212:215], v[20:23]
	v_mfma_f32_16x16x32_bf16 v[12:15], v[158:161], v[212:215], v[12:15]
	s_setprio 0
	s_setprio 1
	v_mfma_f32_16x16x32_bf16 v[48:51], v[162:165], v[178:181], v[48:51]
	v_mfma_f32_16x16x32_bf16 v[40:43], v[170:173], v[178:181], v[40:43]
	v_mfma_f32_16x16x32_bf16 v[32:35], v[162:165], v[186:189], v[32:35]
	v_mfma_f32_16x16x32_bf16 v[24:27], v[170:173], v[186:189], v[24:27]
	v_mfma_f32_16x16x32_bf16 v[16:19], v[162:165], v[200:203], v[16:19]
	v_mfma_f32_16x16x32_bf16 v[8:11], v[170:173], v[200:203], v[8:11]
	v_mfma_f32_16x16x32_bf16 v[4:7], v[162:165], v[208:211], v[4:7]
	v_mfma_f32_16x16x32_bf16 v[0:3], v[170:173], v[208:211], v[0:3]
	v_mfma_f32_16x16x32_bf16 v[48:51], v[166:169], v[182:185], v[48:51]
	v_mfma_f32_16x16x32_bf16 v[40:43], v[174:177], v[182:185], v[40:43]
	v_mfma_f32_16x16x32_bf16 v[32:35], v[166:169], v[190:193], v[32:35]
	v_mfma_f32_16x16x32_bf16 v[24:27], v[174:177], v[190:193], v[24:27]
	v_mfma_f32_16x16x32_bf16 v[16:19], v[166:169], v[204:207], v[16:19]
	v_mfma_f32_16x16x32_bf16 v[8:11], v[174:177], v[204:207], v[8:11]
	v_mfma_f32_16x16x32_bf16 v[4:7], v[166:169], v[212:215], v[4:7]
	v_mfma_f32_16x16x32_bf16 v[0:3], v[174:177], v[212:215], v[0:3]
	s_add_i32 s46, s46, 2
	s_add_u32 s20, s20, 0x100
	s_addc_u32 s21, s21, 0
	s_add_u32 s44, s44, 0x100
	s_addc_u32 s45, s45, 0
	s_cmp_gt_u32 s46, 13
	s_setprio 0
	s_barrier
	s_cbranch_scc0 .LBB0_286
	s_and_b64 vcc, exec, s[10:11]
	s_cbranch_vccz .LBB0_289
	s_barrier

; #define PG8_STAGE(bufoff, gbase, voff) do { _Pragma("unroll") for (int _i = 0; _i < 2; ++_i) \
;         __builtin_amdgcn_global_load_lds((const unsigned*)((const char*)(gbase) + (voff)[_i]), (PG8_LAS unsigned*)(lds + (bufoff) + ldsw + _i * 8192), 16, 0, 0); } while (0)
; #define PG8_LDA(dst, b, h) do { _Pragma("unroll") for (int m = 0; m < 4; ++m) _Pragma("unroll") for (int k = 0; k < 2; ++k) dst[m][k] = *(const PG8_LAS bf16x8*)(lds + PG8_SA(b, h) + aoff + m * 2048 + k * 1024); } while (0)
; #define PG8_LDB(dst, b, h) do { _Pragma("unroll") for (int n = 0; n < 2; ++n) _Pragma("unroll") for (int k = 0; k < 2; ++k) dst[n][k] = *(const PG8_LAS bf16x8*)(lds + PG8_SB(b, h) + boff + n * 2048 + k * 1024); } while (0)
; #define PG8_MMA(ai, bj, At, Bt) do { __builtin_amdgcn_s_setprio(1); _Pragma("unroll") for (int m = 0; m < 4; ++m) _Pragma("unroll") for (int n = 0; n < 2; ++n) _Pragma("unroll") for (int k = 0; k < 2; ++k) \
;         acc[ai][bj][m][n] = __builtin_amdgcn_mfma_f32_16x16x32_bf16(Bt[n][k], At[m][k], acc[ai][bj][m][n], 0, 0, 0); __builtin_amdgcn_s_setprio(0); } while (0)
; #define PG8_WAIT_V(n) asm volatile("s_waitcnt vmcnt(" #n ")" ::: "memory")
; #define PG8_WAIT_L(n) asm volatile("s_waitcnt lgkmcnt(" #n ")" ::: "memory")
; #define PG8_BAR __builtin_amdgcn_s_barrier()
; #define PG8_SCHED __builtin_amdgcn_sched_barrier(0)
; template <class Epi, class Sched, bool ALIGN_EPI = false, bool SP2 = false>
; __device__ __forceinline__ void gemm_phase(PG8_LAS unsigned char* lds, const Gemm g, const Sched& S, const Epi& E, const int tid_in) {
;     ...
;             const bool last = (t == nt - 2);
;             const char* a1 = cA + (size_t)(t + 1) * kstep;
;             const char* a2 = last ? nA : cA + (size_t)(t + 2) * kstep; const char* b2 = last ? nB : cB + (size_t)(t + 2) * kstep;
;             const char* a3 = a2 + kstep; const char* b3 = b2 + kstep;
;             if (last && has_next) S.a_ready(nxt);
;             if constexpr (SP2) {
;             PG8_LDB(B0, 0, 0); PG8_LDB(B1, 0, 1); PG8_SCHED; PG8_LDA(At, 0, 0); PG8_STAGE(PG8_SA(1, 1), a1 + hstepA, voffA);
;             PG8_WAIT_V(8); PG8_WAIT_L(0); PG8_BAR; PG8_MMA(0, 0, At, B0); PG8_MMA(0, 1, At, B1); PG8_BAR; PG8_SCHED;
;             PG8_LDA(At, 0, 1); PG8_STAGE(PG8_SB(0, 0), b2, voffB); PG8_STAGE(PG8_SB(0, 1), b2 + hstepB, voffB); PG8_STAGE(PG8_SA(0, 0), a2, voffA);
.LBB0_689:
	s_add_u32 s30, s28, 0xfffc0080
	s_addc_u32 s31, s29, -1
	s_add_i32 s62, 0, 0x10000
	s_cmp_eq_u32 s61, 12
	s_cselect_b32 s35, s23, s31
	s_cselect_b32 s34, s55, s30
	s_cselect_b32 s31, s21, s60
	s_cselect_b32 s30, s56, s57
	s_add_i32 s64, 0, 0x14000
	v_add_u32_e32 v144, s62, v180
	v_add_u32_e32 v166, s64, v180
	s_waitcnt lgkmcnt(0)
	ds_read_b128 v[132:135], v144
	ds_read_b128 v[136:139], v144 offset:1024
	ds_read_b128 v[140:143], v144 offset:2048
	ds_read_b128 v[144:147], v144 offset:3072
	ds_read_b128 v[154:157], v166
	ds_read_b128 v[158:161], v166 offset:1024
	ds_read_b128 v[162:165], v166 offset:2048
	ds_read_b128 v[166:169], v166 offset:3072
	v_lshl_add_u64 v[178:179], s[28:29], 0, v[150:151]
	s_add_i32 m0, s43, 0xc000
	ds_read_b128 v[170:173], v181
	ds_read_b128 v[174:177], v181 offset:1024
	ds_read_b128 v[182:185], v181 offset:2048
	ds_read_b128 v[186:189], v181 offset:3072
	ds_read_b128 v[190:193], v181 offset:4096
	ds_read_b128 v[200:203], v181 offset:5120
	ds_read_b128 v[204:207], v181 offset:6144
	ds_read_b128 v[208:211], v181 offset:7168
	global_load_lds_dwordx4 v[178:179], off
	v_lshl_add_u64 v[178:179], s[28:29], 0, v[152:153]
	s_add_i32 m0, s43, 0xe000
	s_nop 0
	global_load_lds_dwordx4 v[178:179], off
	s_waitcnt vmcnt(8)
	s_waitcnt lgkmcnt(0)
	s_barrier
	s_setprio 1
	s_waitcnt lgkmcnt(0)
	v_mfma_f32_16x16x32_bf16 v[128:131], v[132:135], v[170:173], v[128:131]
	v_mfma_f32_16x16x32_bf16 v[124:127], v[140:143], v[170:173], v[124:127]
	v_mfma_f32_16x16x32_bf16 v[112:115], v[132:135], v[182:185], v[112:115]
	v_mfma_f32_16x16x32_bf16 v[108:111], v[140:143], v[182:185], v[108:111]
	v_mfma_f32_16x16x32_bf16 v[92:95], v[132:135], v[190:193], v[92:95]
	v_mfma_f32_16x16x32_bf16 v[88:91], v[140:143], v[190:193], v[88:91]
	v_mfma_f32_16x16x32_bf16 v[76:79], v[132:135], v[204:207], v[76:79]
	v_mfma_f32_16x16x32_bf16 v[72:75], v[140:143], v[204:207], v[72:75]
	v_mfma_f32_16x16x32_bf16 v[128:131], v[136:139], v[174:177], v[128:131]
	v_mfma_f32_16x16x32_bf16 v[124:127], v[144:147], v[174:177], v[124:127]
	v_mfma_f32_16x16x32_bf16 v[112:115], v[136:139], v[186:189], v[112:115]
	v_mfma_f32_16x16x32_bf16 v[108:111], v[144:147], v[186:189], v[108:111]
	v_mfma_f32_16x16x32_bf16 v[92:95], v[136:139], v[200:203], v[92:95]
	v_mfma_f32_16x16x32_bf16 v[88:91], v[144:147], v[200:203], v[88:91]
	v_mfma_f32_16x16x32_bf16 v[76:79], v[136:139], v[208:211], v[76:79]
	v_mfma_f32_16x16x32_bf16 v[72:75], v[144:147], v[208:211], v[72:75]
	s_setprio 0
	s_setprio 1
	v_mfma_f32_16x16x32_bf16 v[120:123], v[154:157], v[170:173], v[120:123]
	v_mfma_f32_16x16x32_bf16 v[116:119], v[162:165], v[170:173], v[116:119]
	v_mfma_f32_16x16x32_bf16 v[104:107], v[154:157], v[182:185], v[104:107]
	v_mfma_f32_16x16x32_bf16 v[100:103], v[162:165], v[182:185], v[100:103]
	v_mfma_f32_16x16x32_bf16 v[84:87], v[154:157], v[190:193], v[84:87]
	v_mfma_f32_16x16x32_bf16 v[80:83], v[162:165], v[190:193], v[80:83]
	v_mfma_f32_16x16x32_bf16 v[68:71], v[154:157], v[204:207], v[68:71]
	v_mfma_f32_16x16x32_bf16 v[64:67], v[162:165], v[204:207], v[64:67]
	v_mfma_f32_16x16x32_bf16 v[120:123], v[158:161], v[174:177], v[120:123]
	v_mfma_f32_16x16x32_bf16 v[116:119], v[166:169], v[174:177], v[116:119]
	v_mfma_f32_16x16x32_bf16 v[104:107], v[158:161], v[186:189], v[104:107]
	v_mfma_f32_16x16x32_bf16 v[100:103], v[166:169], v[186:189], v[100:103]
	v_mfma_f32_16x16x32_bf16 v[84:87], v[158:161], v[200:203], v[84:87]
	v_mfma_f32_16x16x32_bf16 v[80:83], v[166:169], v[200:203], v[80:83]
	v_mfma_f32_16x16x32_bf16 v[68:71], v[158:161], v[208:211], v[68:71]
	v_mfma_f32_16x16x32_bf16 v[64:67], v[166:169], v[208:211], v[64:67]
	s_setprio 0
	s_barrier
	s_add_i32 s62, s62, s38
	v_lshl_add_u64 v[178:179], s[30:31], 0, v[148:149]
	s_mov_b32 m0, s62
	ds_read_b128 v[170:173], v181 offset:16384
	ds_read_b128 v[174:177], v181 offset:17408
	ds_read_b128 v[182:185], v181 offset:18432
	ds_read_b128 v[186:189], v181 offset:19456
	ds_read_b128 v[190:193], v181 offset:20480
	ds_read_b128 v[200:203], v181 offset:21504
	ds_read_b128 v[204:207], v181 offset:22528
	ds_read_b128 v[208:211], v181 offset:23552
	global_load_lds_dwordx4 v[178:179], off
	s_add_i32 m0, s62, 0x2000
	s_add_u32 s62, s30, 0x40000
	v_lshl_add_u64 v[194:195], s[30:31], 0, v[96:97]
	s_addc_u32 s63, s31, 0
	s_add_i32 s64, s64, s38
	global_load_lds_dwordx4 v[194:195], off
	v_lshl_add_u64 v[196:197], s[62:63], 0, v[148:149]
	s_mov_b32 m0, s64
	v_lshl_add_u64 v[212:213], s[34:35], 0, v[96:97]
	global_load_lds_dwordx4 v[196:197], off
	v_lshl_add_u64 v[196:197], s[62:63], 0, v[96:97]
	s_add_i32 m0, s64, 0x2000
	s_nop 0
	global_load_lds_dwordx4 v[196:197], off
	v_lshl_add_u64 v[196:197], s[34:35], 0, v[148:149]
	s_mov_b32 m0, s43
	s_nop 0
	global_load_lds_dwordx4 v[196:197], off
	s_mov_b32 m0, s44
	s_nop 0
	global_load_lds_dwordx4 v[212:213], off
	s_waitcnt vmcnt(8)
	s_waitcnt lgkmcnt(0)
	s_barrier
; #define PG8_STAGE(bufoff, gbase, voff) do { _Pragma("unroll") for (int _i = 0; _i < 2; ++_i) \
;         __builtin_amdgcn_global_load_lds((const unsigned*)((const char*)(gbase) + (voff)[_i]), (PG8_LAS unsigned*)(lds + (bufoff) + ldsw + _i * 8192), 16, 0, 0); } while (0)
; #define PG8_LDA(dst, b, h) do { _Pragma("unroll") for (int m = 0; m < 4; ++m) _Pragma("unroll") for (int k = 0; k < 2; ++k) dst[m][k] = *(const PG8_LAS bf16x8*)(lds + PG8_SA(b, h) + aoff + m * 2048 + k * 1024); } while (0)
; #define PG8_LDB(dst, b, h) do { _Pragma("unroll") for (int n = 0; n < 2; ++n) _Pragma("unroll") for (int k = 0; k < 2; ++k) dst[n][k] = *(const PG8_LAS bf16x8*)(lds + PG8_SB(b, h) + boff + n * 2048 + k * 1024); } while (0)
; #define PG8_MMA(ai, bj, At, Bt) do { __builtin_amdgcn_s_setprio(1); _Pragma("unroll") for (int m = 0; m < 4; ++m) _Pragma("unroll") for (int n = 0; n < 2; ++n) _Pragma("unroll") for (int k = 0; k < 2; ++k) \
;         acc[ai][bj][m][n] = __builtin_amdgcn_mfma_f32_16x16x32_bf16(Bt[n][k], At[m][k], acc[ai][bj][m][n], 0, 0, 0); __builtin_amdgcn_s_setprio(0); } while (0)
; #define PG8_WAIT_V(n) asm volatile("s_waitcnt vmcnt(" #n ")" ::: "memory")
; #define PG8_WAIT_L(n) asm volatile("s_waitcnt lgkmcnt(" #n ")" ::: "memory")
; #define PG8_BAR __builtin_amdgcn_s_barrier()
; #define PG8_SCHED __builtin_amdgcn_sched_barrier(0)
; template <class Epi, class Sched, bool ALIGN_EPI = false, bool SP2 = false>
; __device__ __forceinline__ void gemm_phase(PG8_LAS unsigned char* lds, const Gemm g, const Sched& S, const Epi& E, const int tid_in) {
;     ...
;             PG8_WAIT_V(8); PG8_WAIT_L(0); PG8_BAR; PG8_MMA(1, 0, At, B0); PG8_MMA(1, 1, At, B1); PG8_BAR; PG8_SCHED;
;             PG8_LDB(B0, 1, 0); PG8_LDB(B1, 1, 1); PG8_SCHED; PG8_LDA(At, 1, 0); PG8_STAGE(PG8_SA(0, 1), a2 + hstepA, voffA);
;             PG8_WAIT_V(8); PG8_WAIT_L(0); PG8_BAR; PG8_MMA(0, 0, At, B0); PG8_MMA(0, 1, At, B1); PG8_BAR; PG8_SCHED;
	s_setprio 1
	s_waitcnt lgkmcnt(0)
	v_mfma_f32_16x16x32_bf16 v[60:63], v[132:135], v[170:173], v[60:63]
	v_mfma_f32_16x16x32_bf16 v[56:59], v[140:143], v[170:173], v[56:59]
	v_mfma_f32_16x16x32_bf16 v[44:47], v[132:135], v[182:185], v[44:47]
	v_mfma_f32_16x16x32_bf16 v[40:43], v[140:143], v[182:185], v[40:43]
	v_mfma_f32_16x16x32_bf16 v[28:31], v[132:135], v[190:193], v[28:31]
	v_mfma_f32_16x16x32_bf16 v[24:27], v[140:143], v[190:193], v[24:27]
	v_mfma_f32_16x16x32_bf16 v[12:15], v[132:135], v[204:207], v[12:15]
	v_mfma_f32_16x16x32_bf16 v[8:11], v[140:143], v[204:207], v[8:11]
	v_mfma_f32_16x16x32_bf16 v[60:63], v[136:139], v[174:177], v[60:63]
	v_mfma_f32_16x16x32_bf16 v[56:59], v[144:147], v[174:177], v[56:59]
	v_mfma_f32_16x16x32_bf16 v[44:47], v[136:139], v[186:189], v[44:47]
	v_mfma_f32_16x16x32_bf16 v[40:43], v[144:147], v[186:189], v[40:43]
	v_mfma_f32_16x16x32_bf16 v[28:31], v[136:139], v[200:203], v[28:31]
	v_mfma_f32_16x16x32_bf16 v[24:27], v[144:147], v[200:203], v[24:27]
	v_mfma_f32_16x16x32_bf16 v[12:15], v[136:139], v[208:211], v[12:15]
	v_mfma_f32_16x16x32_bf16 v[8:11], v[144:147], v[208:211], v[8:11]
	s_setprio 0
	s_setprio 1
	v_mfma_f32_16x16x32_bf16 v[52:55], v[154:157], v[170:173], v[52:55]
	v_mfma_f32_16x16x32_bf16 v[48:51], v[162:165], v[170:173], v[48:51]
	v_mfma_f32_16x16x32_bf16 v[36:39], v[154:157], v[182:185], v[36:39]
	v_mfma_f32_16x16x32_bf16 v[32:35], v[162:165], v[182:185], v[32:35]
	v_mfma_f32_16x16x32_bf16 v[20:23], v[154:157], v[190:193], v[20:23]
	v_mfma_f32_16x16x32_bf16 v[16:19], v[162:165], v[190:193], v[16:19]
	v_mfma_f32_16x16x32_bf16 v[4:7], v[154:157], v[204:207], v[4:7]
	v_mfma_f32_16x16x32_bf16 v[0:3], v[162:165], v[204:207], v[0:3]
	v_mfma_f32_16x16x32_bf16 v[52:55], v[158:161], v[174:177], v[52:55]
	v_mfma_f32_16x16x32_bf16 v[48:51], v[166:169], v[174:177], v[48:51]
	v_mfma_f32_16x16x32_bf16 v[36:39], v[158:161], v[186:189], v[36:39]
	v_mfma_f32_16x16x32_bf16 v[32:35], v[166:169], v[186:189], v[32:35]
	v_mfma_f32_16x16x32_bf16 v[20:23], v[158:161], v[200:203], v[20:23]
	v_mfma_f32_16x16x32_bf16 v[16:19], v[166:169], v[200:203], v[16:19]
	v_mfma_f32_16x16x32_bf16 v[4:7], v[158:161], v[208:211], v[4:7]
	v_mfma_f32_16x16x32_bf16 v[0:3], v[166:169], v[208:211], v[0:3]
	s_setprio 0
	s_barrier
	s_add_i32 s62, 0, 0x18000
	s_add_i32 s63, 0, 0x1c000
	v_add_u32_e32 v144, s62, v180
	v_add_u32_e32 v166, s63, v180
	ds_read_b128 v[132:135], v144
	ds_read_b128 v[136:139], v144 offset:1024
	ds_read_b128 v[140:143], v144 offset:2048
	ds_read_b128 v[144:147], v144 offset:3072
	ds_read_b128 v[154:157], v166
	ds_read_b128 v[158:161], v166 offset:1024
	ds_read_b128 v[162:165], v166 offset:2048
	ds_read_b128 v[166:169], v166 offset:3072
	s_add_u32 s34, s34, 0x40000
	s_addc_u32 s35, s35, 0
	s_mov_b32 m0, s45
	v_lshl_add_u64 v[214:215], s[34:35], 0, v[148:149]
	ds_read_b128 v[170:173], v181 offset:32768
	ds_read_b128 v[174:177], v181 offset:33792
	ds_read_b128 v[182:185], v181 offset:34816
	ds_read_b128 v[186:189], v181 offset:35840
	ds_read_b128 v[190:193], v181 offset:36864
	ds_read_b128 v[200:203], v181 offset:37888
	ds_read_b128 v[204:207], v181 offset:38912
	ds_read_b128 v[208:211], v181 offset:39936
	global_load_lds_dwordx4 v[214:215], off
	v_lshl_add_u64 v[214:215], s[34:35], 0, v[96:97]
	s_mov_b32 m0, s46
	s_nop 0
	global_load_lds_dwordx4 v[214:215], off
	s_waitcnt vmcnt(8)
	s_waitcnt lgkmcnt(0)
	s_barrier
	s_setprio 1
	s_waitcnt lgkmcnt(0)
	v_mfma_f32_16x16x32_bf16 v[128:131], v[132:135], v[170:173], v[128:131]
	v_mfma_f32_16x16x32_bf16 v[124:127], v[140:143], v[170:173], v[124:127]
	v_mfma_f32_16x16x32_bf16 v[112:115], v[132:135], v[182:185], v[112:115]
	v_mfma_f32_16x16x32_bf16 v[108:111], v[140:143], v[182:185], v[108:111]
	v_mfma_f32_16x16x32_bf16 v[92:95], v[132:135], v[190:193], v[92:95]
	v_mfma_f32_16x16x32_bf16 v[88:91], v[140:143], v[190:193], v[88:91]
	v_mfma_f32_16x16x32_bf16 v[76:79], v[132:135], v[204:207], v[76:79]
	v_mfma_f32_16x16x32_bf16 v[72:75], v[140:143], v[204:207], v[72:75]
	v_mfma_f32_16x16x32_bf16 v[128:131], v[136:139], v[174:177], v[128:131]
	v_mfma_f32_16x16x32_bf16 v[124:127], v[144:147], v[174:177], v[124:127]
	v_mfma_f32_16x16x32_bf16 v[112:115], v[136:139], v[186:189], v[112:115]
	v_mfma_f32_16x16x32_bf16 v[108:111], v[144:147], v[186:189], v[108:111]
	v_mfma_f32_16x16x32_bf16 v[92:95], v[136:139], v[200:203], v[92:95]
	v_mfma_f32_16x16x32_bf16 v[88:91], v[144:147], v[200:203], v[88:91]
	v_mfma_f32_16x16x32_bf16 v[76:79], v[136:139], v[208:211], v[76:79]
	v_mfma_f32_16x16x32_bf16 v[72:75], v[144:147], v[208:211], v[72:75]
	s_setprio 0
	s_setprio 1
	v_mfma_f32_16x16x32_bf16 v[120:123], v[154:157], v[170:173], v[120:123]
	v_mfma_f32_16x16x32_bf16 v[116:119], v[162:165], v[170:173], v[116:119]
	v_mfma_f32_16x16x32_bf16 v[104:107], v[154:157], v[182:185], v[104:107]
	v_mfma_f32_16x16x32_bf16 v[100:103], v[162:165], v[182:185], v[100:103]
	v_mfma_f32_16x16x32_bf16 v[84:87], v[154:157], v[190:193], v[84:87]
	v_mfma_f32_16x16x32_bf16 v[80:83], v[162:165], v[190:193], v[80:83]
	v_mfma_f32_16x16x32_bf16 v[68:71], v[154:157], v[204:207], v[68:71]
	v_mfma_f32_16x16x32_bf16 v[64:67], v[162:165], v[204:207], v[64:67]
	v_mfma_f32_16x16x32_bf16 v[120:123], v[158:161], v[174:177], v[120:123]
	v_mfma_f32_16x16x32_bf16 v[116:119], v[166:169], v[174:177], v[116:119]
	v_mfma_f32_16x16x32_bf16 v[104:107], v[158:161], v[186:189], v[104:107]
	v_mfma_f32_16x16x32_bf16 v[100:103], v[166:169], v[186:189], v[100:103]
	v_mfma_f32_16x16x32_bf16 v[84:87], v[158:161], v[200:203], v[84:87]
	v_mfma_f32_16x16x32_bf16 v[80:83], v[166:169], v[200:203], v[80:83]
	v_mfma_f32_16x16x32_bf16 v[68:71], v[158:161], v[208:211], v[68:71]
	v_mfma_f32_16x16x32_bf16 v[64:67], v[166:169], v[208:211], v[64:67]
	s_setprio 0
	s_barrier
; #define PG8_STAGE(bufoff, gbase, voff) do { _Pragma("unroll") for (int _i = 0; _i < 2; ++_i) \
;         __builtin_amdgcn_global_load_lds((const unsigned*)((const char*)(gbase) + (voff)[_i]), (PG8_LAS unsigned*)(lds + (bufoff) + ldsw + _i * 8192), 16, 0, 0); } while (0)
; #define PG8_LDA(dst, b, h) do { _Pragma("unroll") for (int m = 0; m < 4; ++m) _Pragma("unroll") for (int k = 0; k < 2; ++k) dst[m][k] = *(const PG8_LAS bf16x8*)(lds + PG8_SA(b, h) + aoff + m * 2048 + k * 1024); } while (0)
; #define PG8_MMA(ai, bj, At, Bt) do { __builtin_amdgcn_s_setprio(1); _Pragma("unroll") for (int m = 0; m < 4; ++m) _Pragma("unroll") for (int n = 0; n < 2; ++n) _Pragma("unroll") for (int k = 0; k < 2; ++k) \
;         acc[ai][bj][m][n] = __builtin_amdgcn_mfma_f32_16x16x32_bf16(Bt[n][k], At[m][k], acc[ai][bj][m][n], 0, 0, 0); __builtin_amdgcn_s_setprio(0); } while (0)
; #define PG8_WAIT_V(n) asm volatile("s_waitcnt vmcnt(" #n ")" ::: "memory")
; #define PG8_WAIT_L(n) asm volatile("s_waitcnt lgkmcnt(" #n ")" ::: "memory")
; #define PG8_BAR __builtin_amdgcn_s_barrier()
; #define PG8_SCHED __builtin_amdgcn_sched_barrier(0)
; template <class Epi, class Sched, bool ALIGN_EPI = false, bool SP2 = false>
; __device__ __forceinline__ void gemm_phase(PG8_LAS unsigned char* lds, const Gemm g, const Sched& S, const Epi& E, const int tid_in) {
;     ...
;             PG8_LDA(At, 1, 1); PG8_STAGE(PG8_SB(1, 0), b3, voffB); PG8_STAGE(PG8_SB(1, 1), b3 + hstepB, voffB); PG8_STAGE(PG8_SA(1, 0), a3, voffA);
;             PG8_WAIT_V(8); PG8_WAIT_L(0); PG8_BAR; PG8_MMA(1, 0, At, B0); PG8_MMA(1, 1, At, B1); PG8_BAR; PG8_SCHED;
;     ...
;         if constexpr (ALIGN_EPI) { if (wr == 0) PG8_BAR; }
	s_add_i32 s34, s62, s38
	v_lshl_add_u64 v[178:179], v[178:179], 0, s[50:51]
	s_mov_b32 m0, s34
	ds_read_b128 v[170:173], v181 offset:49152
	ds_read_b128 v[174:177], v181 offset:50176
	ds_read_b128 v[182:185], v181 offset:51200
	ds_read_b128 v[186:189], v181 offset:52224
	ds_read_b128 v[190:193], v181 offset:53248
	ds_read_b128 v[200:203], v181 offset:54272
	ds_read_b128 v[204:207], v181 offset:55296
	ds_read_b128 v[208:211], v181 offset:56320
	global_load_lds_dwordx4 v[178:179], off
	s_add_i32 m0, s34, 0x2000
	s_add_u32 s30, s30, 0x40080
	v_lshl_add_u64 v[178:179], v[194:195], 0, s[50:51]
	s_addc_u32 s31, s31, 0
	s_add_i32 s34, s63, s38
	global_load_lds_dwordx4 v[178:179], off
	v_lshl_add_u64 v[178:179], s[30:31], 0, v[148:149]
	s_mov_b32 m0, s34
	s_nop 0
	global_load_lds_dwordx4 v[178:179], off
	v_lshl_add_u64 v[178:179], s[30:31], 0, v[96:97]
	s_add_i32 m0, s34, 0x2000
	s_nop 0
	global_load_lds_dwordx4 v[178:179], off
	v_lshl_add_u64 v[178:179], v[196:197], 0, s[50:51]
	s_mov_b32 m0, s52
	s_nop 0
	global_load_lds_dwordx4 v[178:179], off
	v_lshl_add_u64 v[178:179], v[212:213], 0, s[50:51]
	s_mov_b32 m0, s53
	s_nop 0
	global_load_lds_dwordx4 v[178:179], off
	s_waitcnt vmcnt(8)
	s_waitcnt lgkmcnt(0)
	s_barrier
	s_setprio 1
	s_waitcnt lgkmcnt(0)
	v_mfma_f32_16x16x32_bf16 v[60:63], v[132:135], v[170:173], v[60:63]
	v_mfma_f32_16x16x32_bf16 v[56:59], v[140:143], v[170:173], v[56:59]
	v_mfma_f32_16x16x32_bf16 v[44:47], v[132:135], v[182:185], v[44:47]
	v_mfma_f32_16x16x32_bf16 v[40:43], v[140:143], v[182:185], v[40:43]
	v_mfma_f32_16x16x32_bf16 v[28:31], v[132:135], v[190:193], v[28:31]
	v_mfma_f32_16x16x32_bf16 v[24:27], v[140:143], v[190:193], v[24:27]
	v_mfma_f32_16x16x32_bf16 v[12:15], v[132:135], v[204:207], v[12:15]
	v_mfma_f32_16x16x32_bf16 v[8:11], v[140:143], v[204:207], v[8:11]
	v_mfma_f32_16x16x32_bf16 v[60:63], v[136:139], v[174:177], v[60:63]
	v_mfma_f32_16x16x32_bf16 v[56:59], v[144:147], v[174:177], v[56:59]
	v_mfma_f32_16x16x32_bf16 v[44:47], v[136:139], v[186:189], v[44:47]
	v_mfma_f32_16x16x32_bf16 v[40:43], v[144:147], v[186:189], v[40:43]
	v_mfma_f32_16x16x32_bf16 v[28:31], v[136:139], v[200:203], v[28:31]
	v_mfma_f32_16x16x32_bf16 v[24:27], v[144:147], v[200:203], v[24:27]
	v_mfma_f32_16x16x32_bf16 v[12:15], v[136:139], v[208:211], v[12:15]
	v_mfma_f32_16x16x32_bf16 v[8:11], v[144:147], v[208:211], v[8:11]
	s_setprio 0
	s_setprio 1
	v_mfma_f32_16x16x32_bf16 v[52:55], v[154:157], v[170:173], v[52:55]
	v_mfma_f32_16x16x32_bf16 v[48:51], v[162:165], v[170:173], v[48:51]
	v_mfma_f32_16x16x32_bf16 v[36:39], v[154:157], v[182:185], v[36:39]
	v_mfma_f32_16x16x32_bf16 v[32:35], v[162:165], v[182:185], v[32:35]
	v_mfma_f32_16x16x32_bf16 v[20:23], v[154:157], v[190:193], v[20:23]
	v_mfma_f32_16x16x32_bf16 v[16:19], v[162:165], v[190:193], v[16:19]
	v_mfma_f32_16x16x32_bf16 v[4:7], v[154:157], v[204:207], v[4:7]
	v_mfma_f32_16x16x32_bf16 v[0:3], v[162:165], v[204:207], v[0:3]
	v_mfma_f32_16x16x32_bf16 v[52:55], v[158:161], v[174:177], v[52:55]
	v_mfma_f32_16x16x32_bf16 v[48:51], v[166:169], v[174:177], v[48:51]
	v_mfma_f32_16x16x32_bf16 v[36:39], v[158:161], v[186:189], v[36:39]
	v_mfma_f32_16x16x32_bf16 v[32:35], v[166:169], v[186:189], v[32:35]
	v_mfma_f32_16x16x32_bf16 v[20:23], v[158:161], v[200:203], v[20:23]
	v_mfma_f32_16x16x32_bf16 v[16:19], v[166:169], v[200:203], v[16:19]
	v_mfma_f32_16x16x32_bf16 v[4:7], v[158:161], v[208:211], v[4:7]
	v_mfma_f32_16x16x32_bf16 v[0:3], v[166:169], v[208:211], v[0:3]
	s_add_i32 s61, s61, 2
	s_add_u32 s28, s28, 0x100
	s_addc_u32 s29, s29, 0
	s_add_u32 s57, s57, 0x100
	s_addc_u32 s60, s60, 0
	s_cmp_gt_u32 s61, 13
	s_setprio 0
	s_barrier
	s_cbranch_scc0 .LBB0_689
	s_and_b64 vcc, exec, s[16:17]
	s_cbranch_vccz .LBB0_692
	s_barrier

; #define PG8_STAGE(bufoff, gbase, voff) do { _Pragma("unroll") for (int _i = 0; _i < 2; ++_i) \
;         __builtin_amdgcn_global_load_lds((const unsigned*)((const char*)(gbase) + (voff)[_i]), (PG8_LAS unsigned*)(lds + (bufoff) + ldsw + _i * 8192), 16, 0, 0); } while (0)
; #define PG8_LDA(dst, b, h) do { _Pragma("unroll") for (int m = 0; m < 4; ++m) _Pragma("unroll") for (int k = 0; k < 2; ++k) dst[m][k] = *(const PG8_LAS bf16x8*)(lds + PG8_SA(b, h) + aoff + m * 2048 + k * 1024); } while (0)
; #define PG8_LDB(dst, b, h) do { _Pragma("unroll") for (int n = 0; n < 2; ++n) _Pragma("unroll") for (int k = 0; k < 2; ++k) dst[n][k] = *(const PG8_LAS bf16x8*)(lds + PG8_SB(b, h) + boff + n * 2048 + k * 1024); } while (0)
; #define PG8_MMA(ai, bj, At, Bt) do { __builtin_amdgcn_s_setprio(1); _Pragma("unroll") for (int m = 0; m < 4; ++m) _Pragma("unroll") for (int n = 0; n < 2; ++n) _Pragma("unroll") for (int k = 0; k < 2; ++k) \
;         acc[ai][bj][m][n] = __builtin_amdgcn_mfma_f32_16x16x32_bf16(Bt[n][k], At[m][k], acc[ai][bj][m][n], 0, 0, 0); __builtin_amdgcn_s_setprio(0); } while (0)
; #define PG8_WAIT_V(n) asm volatile("s_waitcnt vmcnt(" #n ")" ::: "memory")
; #define PG8_WAIT_L(n) asm volatile("s_waitcnt lgkmcnt(" #n ")" ::: "memory")
; #define PG8_BAR __builtin_amdgcn_s_barrier()
; #define PG8_SCHED __builtin_amdgcn_sched_barrier(0)
; template <class Epi, class Sched, bool ALIGN_EPI = false, bool SP2 = false>
; __device__ __forceinline__ void gemm_phase(PG8_LAS unsigned char* lds, const Gemm g, const Sched& S, const Epi& E, const int tid_in) {
;     ...
;             const bool last = (t == nt - 2);
;             const char* a1 = cA + (size_t)(t + 1) * kstep;
;             const char* a2 = last ? nA : cA + (size_t)(t + 2) * kstep; const char* b2 = last ? nB : cB + (size_t)(t + 2) * kstep;
;             const char* a3 = a2 + kstep; const char* b3 = b2 + kstep;
;             if (last && has_next) S.a_ready(nxt);
;             if constexpr (SP2) {
;             PG8_LDB(B0, 0, 0); PG8_LDB(B1, 0, 1); PG8_SCHED; PG8_LDA(At, 0, 0); PG8_STAGE(PG8_SA(1, 1), a1 + hstepA, voffA);
;             PG8_WAIT_V(8); PG8_WAIT_L(0); PG8_BAR; PG8_MMA(0, 0, At, B0); PG8_MMA(0, 1, At, B1); PG8_BAR; PG8_SCHED;
;             PG8_LDA(At, 0, 1); PG8_STAGE(PG8_SB(0, 0), b2, voffB); PG8_STAGE(PG8_SB(0, 1), b2 + hstepB, voffB); PG8_STAGE(PG8_SA(0, 0), a2, voffA);
.LBB0_849:
	s_add_u32 s30, s28, 0xfffc0080
	s_addc_u32 s31, s29, -1
	s_add_i32 s60, 0, 0x10000
	s_cmp_eq_u32 s57, 12
	s_cselect_b32 s35, s23, s31
	s_cselect_b32 s34, s53, s30
	v_add_u32_e32 v142, s60, v143
	s_cselect_b32 s31, s21, s56
	s_cselect_b32 s30, s54, s55
	s_add_i32 s62, 0, 0x14000
	ds_read_b128 v[146:149], v142
	ds_read_b128 v[150:153], v142 offset:1024
	ds_read_b128 v[154:157], v142 offset:2048
	ds_read_b128 v[158:161], v142 offset:3072
	v_add_u32_e32 v142, s62, v143
	ds_read_b128 v[162:165], v142
	ds_read_b128 v[166:169], v142 offset:1024
	ds_read_b128 v[170:173], v142 offset:2048
	ds_read_b128 v[174:177], v142 offset:3072
	v_lshl_add_u64 v[212:213], s[28:29], 0, v[138:139]
	s_add_i32 m0, s41, 0xc000
	ds_read_b128 v[178:181], v145
	ds_read_b128 v[182:185], v145 offset:1024
	ds_read_b128 v[186:189], v145 offset:2048
	ds_read_b128 v[190:193], v145 offset:3072
	ds_read_b128 v[194:197], v145 offset:4096
	ds_read_b128 v[200:203], v145 offset:5120
	ds_read_b128 v[204:207], v145 offset:6144
	ds_read_b128 v[208:211], v145 offset:7168
	global_load_lds_dwordx4 v[212:213], off
	v_lshl_add_u64 v[212:213], s[28:29], 0, v[140:141]
	s_add_i32 m0, s41, 0xe000
	s_nop 0
	global_load_lds_dwordx4 v[212:213], off
	s_waitcnt vmcnt(8)
	s_waitcnt lgkmcnt(0)
	s_barrier
	s_setprio 1
	s_waitcnt lgkmcnt(0)
	v_mfma_f32_16x16x32_bf16 v[128:131], v[146:149], v[178:181], v[128:131]
	v_mfma_f32_16x16x32_bf16 v[124:127], v[154:157], v[178:181], v[124:127]
	v_mfma_f32_16x16x32_bf16 v[112:115], v[146:149], v[186:189], v[112:115]
	v_mfma_f32_16x16x32_bf16 v[108:111], v[154:157], v[186:189], v[108:111]
	v_mfma_f32_16x16x32_bf16 v[92:95], v[146:149], v[194:197], v[92:95]
	v_mfma_f32_16x16x32_bf16 v[88:91], v[154:157], v[194:197], v[88:91]
	v_mfma_f32_16x16x32_bf16 v[76:79], v[146:149], v[204:207], v[76:79]
	v_mfma_f32_16x16x32_bf16 v[72:75], v[154:157], v[204:207], v[72:75]
	v_mfma_f32_16x16x32_bf16 v[128:131], v[150:153], v[182:185], v[128:131]
	v_mfma_f32_16x16x32_bf16 v[124:127], v[158:161], v[182:185], v[124:127]
	v_mfma_f32_16x16x32_bf16 v[112:115], v[150:153], v[190:193], v[112:115]
	v_mfma_f32_16x16x32_bf16 v[108:111], v[158:161], v[190:193], v[108:111]
	v_mfma_f32_16x16x32_bf16 v[92:95], v[150:153], v[200:203], v[92:95]
	v_mfma_f32_16x16x32_bf16 v[88:91], v[158:161], v[200:203], v[88:91]
	v_mfma_f32_16x16x32_bf16 v[76:79], v[150:153], v[208:211], v[76:79]
	v_mfma_f32_16x16x32_bf16 v[72:75], v[158:161], v[208:211], v[72:75]
	s_setprio 0
	s_setprio 1
	v_mfma_f32_16x16x32_bf16 v[120:123], v[162:165], v[178:181], v[120:123]
	v_mfma_f32_16x16x32_bf16 v[116:119], v[170:173], v[178:181], v[116:119]
	v_mfma_f32_16x16x32_bf16 v[104:107], v[162:165], v[186:189], v[104:107]
	v_mfma_f32_16x16x32_bf16 v[100:103], v[170:173], v[186:189], v[100:103]
	v_mfma_f32_16x16x32_bf16 v[84:87], v[162:165], v[194:197], v[84:87]
	v_mfma_f32_16x16x32_bf16 v[80:83], v[170:173], v[194:197], v[80:83]
	v_mfma_f32_16x16x32_bf16 v[68:71], v[162:165], v[204:207], v[68:71]
	v_mfma_f32_16x16x32_bf16 v[64:67], v[170:173], v[204:207], v[64:67]
	v_mfma_f32_16x16x32_bf16 v[120:123], v[166:169], v[182:185], v[120:123]
	v_mfma_f32_16x16x32_bf16 v[116:119], v[174:177], v[182:185], v[116:119]
	v_mfma_f32_16x16x32_bf16 v[104:107], v[166:169], v[190:193], v[104:107]
	v_mfma_f32_16x16x32_bf16 v[100:103], v[174:177], v[190:193], v[100:103]
	v_mfma_f32_16x16x32_bf16 v[84:87], v[166:169], v[200:203], v[84:87]
	v_mfma_f32_16x16x32_bf16 v[80:83], v[174:177], v[200:203], v[80:83]
	v_mfma_f32_16x16x32_bf16 v[68:71], v[166:169], v[208:211], v[68:71]
	v_mfma_f32_16x16x32_bf16 v[64:67], v[174:177], v[208:211], v[64:67]
	s_setprio 0
	s_barrier
	s_add_i32 s60, s60, s40
	v_lshl_add_u64 v[212:213], s[30:31], 0, v[134:135]
	s_mov_b32 m0, s60
	ds_read_b128 v[178:181], v145 offset:16384
	ds_read_b128 v[182:185], v145 offset:17408
	ds_read_b128 v[186:189], v145 offset:18432
	ds_read_b128 v[190:193], v145 offset:19456
	ds_read_b128 v[194:197], v145 offset:20480
	ds_read_b128 v[200:203], v145 offset:21504
	ds_read_b128 v[204:207], v145 offset:22528
	ds_read_b128 v[208:211], v145 offset:23552
	global_load_lds_dwordx4 v[212:213], off
	s_add_i32 m0, s60, 0x2000
	s_add_u32 s60, s30, 0x40000
	v_lshl_add_u64 v[214:215], s[30:31], 0, v[96:97]
	s_addc_u32 s61, s31, 0
	s_add_i32 s62, s62, s40
	global_load_lds_dwordx4 v[214:215], off
	v_lshl_add_u64 v[216:217], s[60:61], 0, v[134:135]
	s_mov_b32 m0, s62
	v_lshl_add_u64 v[218:219], s[34:35], 0, v[132:133]
	global_load_lds_dwordx4 v[216:217], off
	v_lshl_add_u64 v[216:217], s[60:61], 0, v[96:97]
	s_add_i32 m0, s62, 0x2000
	s_nop 0
	global_load_lds_dwordx4 v[216:217], off
	v_lshl_add_u64 v[216:217], s[34:35], 0, v[136:137]
	s_mov_b32 m0, s41
	s_nop 0
	global_load_lds_dwordx4 v[216:217], off
	s_mov_b32 m0, s42
	s_nop 0
	global_load_lds_dwordx4 v[218:219], off
	s_waitcnt vmcnt(8)
	s_waitcnt lgkmcnt(0)
	s_barrier
; #define PG8_STAGE(bufoff, gbase, voff) do { _Pragma("unroll") for (int _i = 0; _i < 2; ++_i) \
;         __builtin_amdgcn_global_load_lds((const unsigned*)((const char*)(gbase) + (voff)[_i]), (PG8_LAS unsigned*)(lds + (bufoff) + ldsw + _i * 8192), 16, 0, 0); } while (0)
; #define PG8_LDA(dst, b, h) do { _Pragma("unroll") for (int m = 0; m < 4; ++m) _Pragma("unroll") for (int k = 0; k < 2; ++k) dst[m][k] = *(const PG8_LAS bf16x8*)(lds + PG8_SA(b, h) + aoff + m * 2048 + k * 1024); } while (0)
; #define PG8_LDB(dst, b, h) do { _Pragma("unroll") for (int n = 0; n < 2; ++n) _Pragma("unroll") for (int k = 0; k < 2; ++k) dst[n][k] = *(const PG8_LAS bf16x8*)(lds + PG8_SB(b, h) + boff + n * 2048 + k * 1024); } while (0)
; #define PG8_MMA(ai, bj, At, Bt) do { __builtin_amdgcn_s_setprio(1); _Pragma("unroll") for (int m = 0; m < 4; ++m) _Pragma("unroll") for (int n = 0; n < 2; ++n) _Pragma("unroll") for (int k = 0; k < 2; ++k) \
;         acc[ai][bj][m][n] = __builtin_amdgcn_mfma_f32_16x16x32_bf16(Bt[n][k], At[m][k], acc[ai][bj][m][n], 0, 0, 0); __builtin_amdgcn_s_setprio(0); } while (0)
; #define PG8_BAR __builtin_amdgcn_s_barrier()
; template <class Epi, class Sched, bool ALIGN_EPI = false, bool SP2 = false>
; __device__ __forceinline__ void gemm_phase(PG8_LAS unsigned char* lds, const Gemm g, const Sched& S, const Epi& E, const int tid_in) {
;     ...
;             PG8_LDB(B0, 0, 0); PG8_LDB(B1, 0, 1); PG8_SCHED; PG8_LDA(At, 0, 0); PG8_STAGE(PG8_SA(1, 1), a1 + hstepA, voffA);
;             PG8_WAIT_V(8); PG8_WAIT_L(0); PG8_BAR; PG8_MMA(0, 0, At, B0); PG8_MMA(0, 1, At, B1); PG8_BAR; PG8_SCHED;
;             PG8_LDA(At, 0, 1); PG8_STAGE(PG8_SB(0, 0), b2, voffB); PG8_STAGE(PG8_SB(0, 1), b2 + hstepB, voffB); PG8_STAGE(PG8_SA(0, 0), a2, voffA);
;             PG8_WAIT_V(8); PG8_WAIT_L(0); PG8_BAR; PG8_MMA(1, 0, At, B0); PG8_MMA(1, 1, At, B1); PG8_BAR; PG8_SCHED;
;             PG8_LDB(B0, 1, 0); PG8_LDB(B1, 1, 1); PG8_SCHED; PG8_LDA(At, 1, 0); PG8_STAGE(PG8_SA(0, 1), a2 + hstepA, voffA);
;             PG8_WAIT_V(8); PG8_WAIT_L(0); PG8_BAR; PG8_MMA(0, 0, At, B0); PG8_MMA(0, 1, At, B1); PG8_BAR; PG8_SCHED;
;             PG8_LDA(At, 1, 1); PG8_STAGE(PG8_SB(1, 0), b3, voffB); PG8_STAGE(PG8_SB(1, 1), b3 + hstepB, voffB); PG8_STAGE(PG8_SA(1, 0), a3, voffA);
;             PG8_WAIT_V(8); PG8_WAIT_L(0); PG8_BAR; PG8_MMA(1, 0, At, B0); PG8_MMA(1, 1, At, B1); PG8_BAR; PG8_SCHED;
	s_setprio 1
	s_waitcnt lgkmcnt(0)
	v_mfma_f32_16x16x32_bf16 v[60:63], v[146:149], v[178:181], v[60:63]
	v_mfma_f32_16x16x32_bf16 v[56:59], v[154:157], v[178:181], v[56:59]
	v_mfma_f32_16x16x32_bf16 v[52:55], v[146:149], v[186:189], v[52:55]
	v_mfma_f32_16x16x32_bf16 v[44:47], v[154:157], v[186:189], v[44:47]
	v_mfma_f32_16x16x32_bf16 v[36:39], v[146:149], v[194:197], v[36:39]
	v_mfma_f32_16x16x32_bf16 v[28:31], v[154:157], v[194:197], v[28:31]
	v_mfma_f32_16x16x32_bf16 v[20:23], v[146:149], v[204:207], v[20:23]
	v_mfma_f32_16x16x32_bf16 v[12:15], v[154:157], v[204:207], v[12:15]
	v_mfma_f32_16x16x32_bf16 v[60:63], v[150:153], v[182:185], v[60:63]
	v_mfma_f32_16x16x32_bf16 v[56:59], v[158:161], v[182:185], v[56:59]
	v_mfma_f32_16x16x32_bf16 v[52:55], v[150:153], v[190:193], v[52:55]
	v_mfma_f32_16x16x32_bf16 v[44:47], v[158:161], v[190:193], v[44:47]
	v_mfma_f32_16x16x32_bf16 v[36:39], v[150:153], v[200:203], v[36:39]
	v_mfma_f32_16x16x32_bf16 v[28:31], v[158:161], v[200:203], v[28:31]
	v_mfma_f32_16x16x32_bf16 v[20:23], v[150:153], v[208:211], v[20:23]
	v_mfma_f32_16x16x32_bf16 v[12:15], v[158:161], v[208:211], v[12:15]
	s_setprio 0
	s_setprio 1
	v_mfma_f32_16x16x32_bf16 v[48:51], v[162:165], v[178:181], v[48:51]
	v_mfma_f32_16x16x32_bf16 v[40:43], v[170:173], v[178:181], v[40:43]
	v_mfma_f32_16x16x32_bf16 v[32:35], v[162:165], v[186:189], v[32:35]
	v_mfma_f32_16x16x32_bf16 v[24:27], v[170:173], v[186:189], v[24:27]
	v_mfma_f32_16x16x32_bf16 v[16:19], v[162:165], v[194:197], v[16:19]
	v_mfma_f32_16x16x32_bf16 v[8:11], v[170:173], v[194:197], v[8:11]
	v_mfma_f32_16x16x32_bf16 v[4:7], v[162:165], v[204:207], v[4:7]
	v_mfma_f32_16x16x32_bf16 v[0:3], v[170:173], v[204:207], v[0:3]
	v_mfma_f32_16x16x32_bf16 v[48:51], v[166:169], v[182:185], v[48:51]
	v_mfma_f32_16x16x32_bf16 v[40:43], v[174:177], v[182:185], v[40:43]
	v_mfma_f32_16x16x32_bf16 v[32:35], v[166:169], v[190:193], v[32:35]
	v_mfma_f32_16x16x32_bf16 v[24:27], v[174:177], v[190:193], v[24:27]
	v_mfma_f32_16x16x32_bf16 v[16:19], v[166:169], v[200:203], v[16:19]
	v_mfma_f32_16x16x32_bf16 v[8:11], v[174:177], v[200:203], v[8:11]
	v_mfma_f32_16x16x32_bf16 v[4:7], v[166:169], v[208:211], v[4:7]
	v_mfma_f32_16x16x32_bf16 v[0:3], v[174:177], v[208:211], v[0:3]
	s_setprio 0
	s_barrier
	s_add_i32 s60, 0, 0x18000
	v_add_u32_e32 v142, s60, v143
	s_add_i32 s61, 0, 0x1c000
	ds_read_b128 v[146:149], v142
	ds_read_b128 v[150:153], v142 offset:1024
	ds_read_b128 v[154:157], v142 offset:2048
	ds_read_b128 v[158:161], v142 offset:3072
	v_add_u32_e32 v142, s61, v143
	ds_read_b128 v[162:165], v142
	ds_read_b128 v[166:169], v142 offset:1024
	ds_read_b128 v[170:173], v142 offset:2048
	ds_read_b128 v[174:177], v142 offset:3072
	s_add_u32 s34, s34, 0x40000
	s_addc_u32 s35, s35, 0
	s_mov_b32 m0, s43
	v_lshl_add_u64 v[220:221], s[34:35], 0, v[136:137]
	ds_read_b128 v[178:181], v145 offset:32768
	ds_read_b128 v[182:185], v145 offset:33792
	ds_read_b128 v[186:189], v145 offset:34816
	ds_read_b128 v[190:193], v145 offset:35840
	ds_read_b128 v[194:197], v145 offset:36864
	ds_read_b128 v[200:203], v145 offset:37888
	ds_read_b128 v[204:207], v145 offset:38912
	ds_read_b128 v[208:211], v145 offset:39936
	global_load_lds_dwordx4 v[220:221], off
	v_lshl_add_u64 v[220:221], s[34:35], 0, v[132:133]
	s_mov_b32 m0, s44
	s_nop 0
	global_load_lds_dwordx4 v[220:221], off
	s_waitcnt vmcnt(8)
	s_waitcnt lgkmcnt(0)
	s_barrier
	s_setprio 1
	s_waitcnt lgkmcnt(0)
	v_mfma_f32_16x16x32_bf16 v[128:131], v[146:149], v[178:181], v[128:131]
	v_mfma_f32_16x16x32_bf16 v[124:127], v[154:157], v[178:181], v[124:127]
	v_mfma_f32_16x16x32_bf16 v[112:115], v[146:149], v[186:189], v[112:115]
	v_mfma_f32_16x16x32_bf16 v[108:111], v[154:157], v[186:189], v[108:111]
	v_mfma_f32_16x16x32_bf16 v[92:95], v[146:149], v[194:197], v[92:95]
	v_mfma_f32_16x16x32_bf16 v[88:91], v[154:157], v[194:197], v[88:91]
	v_mfma_f32_16x16x32_bf16 v[76:79], v[146:149], v[204:207], v[76:79]
	v_mfma_f32_16x16x32_bf16 v[72:75], v[154:157], v[204:207], v[72:75]
	v_mfma_f32_16x16x32_bf16 v[128:131], v[150:153], v[182:185], v[128:131]
	v_mfma_f32_16x16x32_bf16 v[124:127], v[158:161], v[182:185], v[124:127]
	v_mfma_f32_16x16x32_bf16 v[112:115], v[150:153], v[190:193], v[112:115]
	v_mfma_f32_16x16x32_bf16 v[108:111], v[158:161], v[190:193], v[108:111]
	v_mfma_f32_16x16x32_bf16 v[92:95], v[150:153], v[200:203], v[92:95]
	v_mfma_f32_16x16x32_bf16 v[88:91], v[158:161], v[200:203], v[88:91]
	v_mfma_f32_16x16x32_bf16 v[76:79], v[150:153], v[208:211], v[76:79]
	v_mfma_f32_16x16x32_bf16 v[72:75], v[158:161], v[208:211], v[72:75]
	s_setprio 0
	s_setprio 1
	v_mfma_f32_16x16x32_bf16 v[120:123], v[162:165], v[178:181], v[120:123]
	v_mfma_f32_16x16x32_bf16 v[116:119], v[170:173], v[178:181], v[116:119]
	v_mfma_f32_16x16x32_bf16 v[104:107], v[162:165], v[186:189], v[104:107]
	v_mfma_f32_16x16x32_bf16 v[100:103], v[170:173], v[186:189], v[100:103]
	v_mfma_f32_16x16x32_bf16 v[84:87], v[162:165], v[194:197], v[84:87]
	v_mfma_f32_16x16x32_bf16 v[80:83], v[170:173], v[194:197], v[80:83]
	v_mfma_f32_16x16x32_bf16 v[68:71], v[162:165], v[204:207], v[68:71]
	v_mfma_f32_16x16x32_bf16 v[64:67], v[170:173], v[204:207], v[64:67]
	v_mfma_f32_16x16x32_bf16 v[120:123], v[166:169], v[182:185], v[120:123]
	v_mfma_f32_16x16x32_bf16 v[116:119], v[174:177], v[182:185], v[116:119]
	v_mfma_f32_16x16x32_bf16 v[104:107], v[166:169], v[190:193], v[104:107]
	v_mfma_f32_16x16x32_bf16 v[100:103], v[174:177], v[190:193], v[100:103]
	v_mfma_f32_16x16x32_bf16 v[84:87], v[166:169], v[200:203], v[84:87]
	v_mfma_f32_16x16x32_bf16 v[80:83], v[174:177], v[200:203], v[80:83]
	v_mfma_f32_16x16x32_bf16 v[68:71], v[166:169], v[208:211], v[68:71]
	v_mfma_f32_16x16x32_bf16 v[64:67], v[174:177], v[208:211], v[64:67]
	s_setprio 0
	s_barrier
; #define PG8_STAGE(bufoff, gbase, voff) do { _Pragma("unroll") for (int _i = 0; _i < 2; ++_i) \
;         __builtin_amdgcn_global_load_lds((const unsigned*)((const char*)(gbase) + (voff)[_i]), (PG8_LAS unsigned*)(lds + (bufoff) + ldsw + _i * 8192), 16, 0, 0); } while (0)
; #define PG8_LDA(dst, b, h) do { _Pragma("unroll") for (int m = 0; m < 4; ++m) _Pragma("unroll") for (int k = 0; k < 2; ++k) dst[m][k] = *(const PG8_LAS bf16x8*)(lds + PG8_SA(b, h) + aoff + m * 2048 + k * 1024); } while (0)
; #define PG8_MMA(ai, bj, At, Bt) do { __builtin_amdgcn_s_setprio(1); _Pragma("unroll") for (int m = 0; m < 4; ++m) _Pragma("unroll") for (int n = 0; n < 2; ++n) _Pragma("unroll") for (int k = 0; k < 2; ++k) \
;         acc[ai][bj][m][n] = __builtin_amdgcn_mfma_f32_16x16x32_bf16(Bt[n][k], At[m][k], acc[ai][bj][m][n], 0, 0, 0); __builtin_amdgcn_s_setprio(0); } while (0)
; #define PG8_WAIT_V(n) asm volatile("s_waitcnt vmcnt(" #n ")" ::: "memory")
; #define PG8_WAIT_L(n) asm volatile("s_waitcnt lgkmcnt(" #n ")" ::: "memory")
; #define PG8_BAR __builtin_amdgcn_s_barrier()
; #define PG8_SCHED __builtin_amdgcn_sched_barrier(0)
; template <class Epi, class Sched, bool ALIGN_EPI = false, bool SP2 = false>
; __device__ __forceinline__ void gemm_phase(PG8_LAS unsigned char* lds, const Gemm g, const Sched& S, const Epi& E, const int tid_in) {
;     ...
;         for (int t = 0; t < nt; t += 2) {
;             const bool last = (t == nt - 2);
;             const char* a1 = cA + (size_t)(t + 1) * kstep;
;             const char* a2 = last ? nA : cA + (size_t)(t + 2) * kstep; const char* b2 = last ? nB : cB + (size_t)(t + 2) * kstep;
;             const char* a3 = a2 + kstep; const char* b3 = b2 + kstep;
;             if (last && has_next) S.a_ready(nxt);
;     ...
;             PG8_LDA(At, 1, 1); PG8_STAGE(PG8_SB(1, 0), b3, voffB); PG8_STAGE(PG8_SB(1, 1), b3 + hstepB, voffB); PG8_STAGE(PG8_SA(1, 0), a3, voffA);
;             PG8_WAIT_V(8); PG8_WAIT_L(0); PG8_BAR; PG8_MMA(1, 0, At, B0); PG8_MMA(1, 1, At, B1); PG8_BAR; PG8_SCHED;
	s_add_i32 s34, s60, s40
	v_lshl_add_u64 v[212:213], v[212:213], 0, s[50:51]
	s_mov_b32 m0, s34
	ds_read_b128 v[178:181], v145 offset:49152
	ds_read_b128 v[182:185], v145 offset:50176
	ds_read_b128 v[186:189], v145 offset:51200
	ds_read_b128 v[190:193], v145 offset:52224
	ds_read_b128 v[194:197], v145 offset:53248
	ds_read_b128 v[200:203], v145 offset:54272
	ds_read_b128 v[204:207], v145 offset:55296
	ds_read_b128 v[208:211], v145 offset:56320
	global_load_lds_dwordx4 v[212:213], off
	s_add_i32 m0, s34, 0x2000
	s_add_u32 s30, s30, 0x40080
	v_lshl_add_u64 v[212:213], v[214:215], 0, s[50:51]
	s_addc_u32 s31, s31, 0
	s_add_i32 s34, s61, s40
	global_load_lds_dwordx4 v[212:213], off
	v_lshl_add_u64 v[212:213], s[30:31], 0, v[134:135]
	s_mov_b32 m0, s34
	s_nop 0
	global_load_lds_dwordx4 v[212:213], off
	v_lshl_add_u64 v[212:213], s[30:31], 0, v[96:97]
	s_add_i32 m0, s34, 0x2000
	s_nop 0
	global_load_lds_dwordx4 v[212:213], off
	v_lshl_add_u64 v[212:213], v[216:217], 0, s[50:51]
	s_mov_b32 m0, s46
	s_nop 0
	global_load_lds_dwordx4 v[212:213], off
	v_lshl_add_u64 v[212:213], v[218:219], 0, s[50:51]
	s_mov_b32 m0, s47
	s_nop 0
	global_load_lds_dwordx4 v[212:213], off
	s_waitcnt vmcnt(8)
	s_waitcnt lgkmcnt(0)
	s_barrier
	s_setprio 1
	s_waitcnt lgkmcnt(0)
	v_mfma_f32_16x16x32_bf16 v[60:63], v[146:149], v[178:181], v[60:63]
	v_mfma_f32_16x16x32_bf16 v[56:59], v[154:157], v[178:181], v[56:59]
	v_mfma_f32_16x16x32_bf16 v[52:55], v[146:149], v[186:189], v[52:55]
	v_mfma_f32_16x16x32_bf16 v[44:47], v[154:157], v[186:189], v[44:47]
	v_mfma_f32_16x16x32_bf16 v[36:39], v[146:149], v[194:197], v[36:39]
	v_mfma_f32_16x16x32_bf16 v[28:31], v[154:157], v[194:197], v[28:31]
	v_mfma_f32_16x16x32_bf16 v[20:23], v[146:149], v[204:207], v[20:23]
	v_mfma_f32_16x16x32_bf16 v[12:15], v[154:157], v[204:207], v[12:15]
	v_mfma_f32_16x16x32_bf16 v[60:63], v[150:153], v[182:185], v[60:63]
	v_mfma_f32_16x16x32_bf16 v[56:59], v[158:161], v[182:185], v[56:59]
	v_mfma_f32_16x16x32_bf16 v[52:55], v[150:153], v[190:193], v[52:55]
	v_mfma_f32_16x16x32_bf16 v[44:47], v[158:161], v[190:193], v[44:47]
	v_mfma_f32_16x16x32_bf16 v[36:39], v[150:153], v[200:203], v[36:39]
	v_mfma_f32_16x16x32_bf16 v[28:31], v[158:161], v[200:203], v[28:31]
	v_mfma_f32_16x16x32_bf16 v[20:23], v[150:153], v[208:211], v[20:23]
	v_mfma_f32_16x16x32_bf16 v[12:15], v[158:161], v[208:211], v[12:15]
	s_setprio 0
	s_setprio 1
	v_mfma_f32_16x16x32_bf16 v[48:51], v[162:165], v[178:181], v[48:51]
	v_mfma_f32_16x16x32_bf16 v[40:43], v[170:173], v[178:181], v[40:43]
	v_mfma_f32_16x16x32_bf16 v[32:35], v[162:165], v[186:189], v[32:35]
	v_mfma_f32_16x16x32_bf16 v[24:27], v[170:173], v[186:189], v[24:27]
	v_mfma_f32_16x16x32_bf16 v[16:19], v[162:165], v[194:197], v[16:19]
	v_mfma_f32_16x16x32_bf16 v[8:11], v[170:173], v[194:197], v[8:11]
	v_mfma_f32_16x16x32_bf16 v[4:7], v[162:165], v[204:207], v[4:7]
	v_mfma_f32_16x16x32_bf16 v[0:3], v[170:173], v[204:207], v[0:3]
	v_mfma_f32_16x16x32_bf16 v[48:51], v[166:169], v[182:185], v[48:51]
	v_mfma_f32_16x16x32_bf16 v[40:43], v[174:177], v[182:185], v[40:43]
	v_mfma_f32_16x16x32_bf16 v[32:35], v[166:169], v[190:193], v[32:35]
	v_mfma_f32_16x16x32_bf16 v[24:27], v[174:177], v[190:193], v[24:27]
	v_mfma_f32_16x16x32_bf16 v[16:19], v[166:169], v[200:203], v[16:19]
	v_mfma_f32_16x16x32_bf16 v[8:11], v[174:177], v[200:203], v[8:11]
	v_mfma_f32_16x16x32_bf16 v[4:7], v[166:169], v[208:211], v[4:7]
	v_mfma_f32_16x16x32_bf16 v[0:3], v[174:177], v[208:211], v[0:3]
	s_add_i32 s57, s57, 2
	s_add_u32 s28, s28, 0x100
	s_addc_u32 s29, s29, 0
	s_add_u32 s55, s55, 0x100
	s_addc_u32 s56, s56, 0
	s_cmp_gt_u32 s57, 13
	s_setprio 0
	s_barrier
	s_cbranch_scc0 .LBB0_849
	s_and_b64 vcc, exec, s[18:19]
	s_cbranch_vccz .LBB0_852
	s_barrier

; #define PG8_STAGE(bufoff, gbase, voff) do { _Pragma("unroll") for (int _i = 0; _i < 2; ++_i) \
;         __builtin_amdgcn_global_load_lds((const unsigned*)((const char*)(gbase) + (voff)[_i]), (PG8_LAS unsigned*)(lds + (bufoff) + ldsw + _i * 8192), 16, 0, 0); } while (0)
; #define PG8_LDA(dst, b, h) do { _Pragma("unroll") for (int m = 0; m < 4; ++m) _Pragma("unroll") for (int k = 0; k < 2; ++k) dst[m][k] = *(const PG8_LAS bf16x8*)(lds + PG8_SA(b, h) + aoff + m * 2048 + k * 1024); } while (0)
; #define PG8_LDB(dst, b, h) do { _Pragma("unroll") for (int n = 0; n < 2; ++n) _Pragma("unroll") for (int k = 0; k < 2; ++k) dst[n][k] = *(const PG8_LAS bf16x8*)(lds + PG8_SB(b, h) + boff + n * 2048 + k * 1024); } while (0)
; #define PG8_MMA(ai, bj, At, Bt) do { __builtin_amdgcn_s_setprio(1); _Pragma("unroll") for (int m = 0; m < 4; ++m) _Pragma("unroll") for (int n = 0; n < 2; ++n) _Pragma("unroll") for (int k = 0; k < 2; ++k) \
;         acc[ai][bj][m][n] = __builtin_amdgcn_mfma_f32_16x16x32_bf16(Bt[n][k], At[m][k], acc[ai][bj][m][n], 0, 0, 0); __builtin_amdgcn_s_setprio(0); } while (0)
; #define PG8_WAIT_V(n) asm volatile("s_waitcnt vmcnt(" #n ")" ::: "memory")
; #define PG8_BAR __builtin_amdgcn_s_barrier()
; template <class Epi, class Sched, bool ALIGN_EPI = false, bool SP2 = false>
; __device__ __forceinline__ void gemm_phase(PG8_LAS unsigned char* lds, const Gemm g, const Sched& S, const Epi& E, const int tid_in) {
;     ...
;         for (int t = 0; t < nt; t += 2) {
;             const bool last = (t == nt - 2);
;             const char* a1 = cA + (size_t)(t + 1) * kstep;
;             const char* a2 = last ? nA : cA + (size_t)(t + 2) * kstep; const char* b2 = last ? nB : cB + (size_t)(t + 2) * kstep;
;             const char* a3 = a2 + kstep; const char* b3 = b2 + kstep;
;             if (last && has_next) S.a_ready(nxt);
;             if constexpr (SP2) {
;             PG8_LDB(B0, 0, 0); PG8_LDB(B1, 0, 1); PG8_SCHED; PG8_LDA(At, 0, 0); PG8_STAGE(PG8_SA(1, 1), a1 + hstepA, voffA);
;             PG8_WAIT_V(8); PG8_WAIT_L(0); PG8_BAR; PG8_MMA(0, 0, At, B0); PG8_MMA(0, 1, At, B1); PG8_BAR; PG8_SCHED;
;             PG8_LDA(At, 0, 1); PG8_STAGE(PG8_SB(0, 0), b2, voffB); PG8_STAGE(PG8_SB(0, 1), b2 + hstepB, voffB); PG8_STAGE(PG8_SA(0, 0), a2, voffA);
;             PG8_WAIT_V(8); PG8_WAIT_L(0); PG8_BAR; PG8_MMA(1, 0, At, B0); PG8_MMA(1, 1, At, B1); PG8_BAR; PG8_SCHED;
.LBB0_1131:
	s_add_u32 s22, s20, 0xfffc0080
	s_addc_u32 s23, s21, -1
	s_add_i32 s49, 0, 0x10000
	s_cmp_eq_u32 s48, 12
	s_cselect_b32 s25, s15, s23
	s_cselect_b32 s24, s44, s22
	v_add_u32_e32 v142, s49, v143
	s_cselect_b32 s23, s13, s47
	s_cselect_b32 s22, s45, s46
	s_add_i32 s54, 0, 0x14000
	ds_read_b128 v[148:151], v142
	ds_read_b128 v[152:155], v142 offset:1024
	ds_read_b128 v[156:159], v142 offset:2048
	ds_read_b128 v[160:163], v142 offset:3072
	v_add_u32_e32 v142, s54, v143
	ds_read_b128 v[164:167], v142
	ds_read_b128 v[168:171], v142 offset:1024
	ds_read_b128 v[172:175], v142 offset:2048
	ds_read_b128 v[176:179], v142 offset:3072
	v_lshl_add_u64 v[144:145], s[20:21], 0, v[138:139]
	s_add_i32 m0, s31, 0xc000
	ds_read_b128 v[180:183], v147
	ds_read_b128 v[184:187], v147 offset:1024
	ds_read_b128 v[188:191], v147 offset:2048
	ds_read_b128 v[192:195], v147 offset:3072
	ds_read_b128 v[200:203], v147 offset:4096
	ds_read_b128 v[204:207], v147 offset:5120
	ds_read_b128 v[208:211], v147 offset:6144
	ds_read_b128 v[212:215], v147 offset:7168
	global_load_lds_dwordx4 v[144:145], off
	v_lshl_add_u64 v[144:145], s[20:21], 0, v[140:141]
	s_add_i32 m0, s31, 0xe000
	s_nop 0
	global_load_lds_dwordx4 v[144:145], off
	s_waitcnt vmcnt(8)
	s_waitcnt lgkmcnt(0)
	s_barrier
	s_setprio 1
	s_waitcnt lgkmcnt(0)
	v_mfma_f32_16x16x32_bf16 v[128:131], v[148:151], v[180:183], v[128:131]
	v_mfma_f32_16x16x32_bf16 v[124:127], v[156:159], v[180:183], v[124:127]
	v_mfma_f32_16x16x32_bf16 v[112:115], v[148:151], v[188:191], v[112:115]
	v_mfma_f32_16x16x32_bf16 v[108:111], v[156:159], v[188:191], v[108:111]
	v_mfma_f32_16x16x32_bf16 v[92:95], v[148:151], v[200:203], v[92:95]
	v_mfma_f32_16x16x32_bf16 v[88:91], v[156:159], v[200:203], v[88:91]
	v_mfma_f32_16x16x32_bf16 v[76:79], v[148:151], v[208:211], v[76:79]
	v_mfma_f32_16x16x32_bf16 v[72:75], v[156:159], v[208:211], v[72:75]
	v_mfma_f32_16x16x32_bf16 v[128:131], v[152:155], v[184:187], v[128:131]
	v_mfma_f32_16x16x32_bf16 v[124:127], v[160:163], v[184:187], v[124:127]
	v_mfma_f32_16x16x32_bf16 v[112:115], v[152:155], v[192:195], v[112:115]
	v_mfma_f32_16x16x32_bf16 v[108:111], v[160:163], v[192:195], v[108:111]
	v_mfma_f32_16x16x32_bf16 v[92:95], v[152:155], v[204:207], v[92:95]
	v_mfma_f32_16x16x32_bf16 v[88:91], v[160:163], v[204:207], v[88:91]
	v_mfma_f32_16x16x32_bf16 v[76:79], v[152:155], v[212:215], v[76:79]
	v_mfma_f32_16x16x32_bf16 v[72:75], v[160:163], v[212:215], v[72:75]
	s_setprio 0
	s_setprio 1
	v_mfma_f32_16x16x32_bf16 v[120:123], v[164:167], v[180:183], v[120:123]
	v_mfma_f32_16x16x32_bf16 v[116:119], v[172:175], v[180:183], v[116:119]
	v_mfma_f32_16x16x32_bf16 v[104:107], v[164:167], v[188:191], v[104:107]
	v_mfma_f32_16x16x32_bf16 v[100:103], v[172:175], v[188:191], v[100:103]
	v_mfma_f32_16x16x32_bf16 v[84:87], v[164:167], v[200:203], v[84:87]
	v_mfma_f32_16x16x32_bf16 v[80:83], v[172:175], v[200:203], v[80:83]
	v_mfma_f32_16x16x32_bf16 v[68:71], v[164:167], v[208:211], v[68:71]
	v_mfma_f32_16x16x32_bf16 v[64:67], v[172:175], v[208:211], v[64:67]
	v_mfma_f32_16x16x32_bf16 v[120:123], v[168:171], v[184:187], v[120:123]
	v_mfma_f32_16x16x32_bf16 v[116:119], v[176:179], v[184:187], v[116:119]
	v_mfma_f32_16x16x32_bf16 v[104:107], v[168:171], v[192:195], v[104:107]
	v_mfma_f32_16x16x32_bf16 v[100:103], v[176:179], v[192:195], v[100:103]
	v_mfma_f32_16x16x32_bf16 v[84:87], v[168:171], v[204:207], v[84:87]
	v_mfma_f32_16x16x32_bf16 v[80:83], v[176:179], v[204:207], v[80:83]
	v_mfma_f32_16x16x32_bf16 v[68:71], v[168:171], v[212:215], v[68:71]
	v_mfma_f32_16x16x32_bf16 v[64:67], v[176:179], v[212:215], v[64:67]
	s_setprio 0
	s_barrier
	s_add_i32 s49, s49, s30
	v_lshl_add_u64 v[144:145], s[22:23], 0, v[134:135]
	s_mov_b32 m0, s49
	ds_read_b128 v[180:183], v147 offset:16384
	ds_read_b128 v[184:187], v147 offset:17408
	ds_read_b128 v[188:191], v147 offset:18432
	ds_read_b128 v[192:195], v147 offset:19456
	ds_read_b128 v[200:203], v147 offset:20480
	ds_read_b128 v[204:207], v147 offset:21504
	ds_read_b128 v[208:211], v147 offset:22528
	ds_read_b128 v[212:215], v147 offset:23552
	global_load_lds_dwordx4 v[144:145], off
	s_add_i32 m0, s49, 0x2000
	s_add_u32 s52, s22, 0x40000
	v_lshl_add_u64 v[196:197], s[22:23], 0, v[96:97]
	s_addc_u32 s53, s23, 0
	s_add_i32 s49, s54, s30
	global_load_lds_dwordx4 v[196:197], off
	v_lshl_add_u64 v[216:217], s[52:53], 0, v[134:135]
	s_mov_b32 m0, s49
	v_lshl_add_u64 v[218:219], s[24:25], 0, v[132:133]
	global_load_lds_dwordx4 v[216:217], off
	v_lshl_add_u64 v[216:217], s[52:53], 0, v[96:97]
	s_add_i32 m0, s49, 0x2000
	s_nop 0
	global_load_lds_dwordx4 v[216:217], off
	v_lshl_add_u64 v[216:217], s[24:25], 0, v[136:137]
	s_mov_b32 m0, s31
	s_nop 0
	global_load_lds_dwordx4 v[216:217], off
	s_mov_b32 m0, s34
	s_nop 0
	global_load_lds_dwordx4 v[218:219], off
	s_waitcnt vmcnt(8)
	s_waitcnt lgkmcnt(0)
	s_barrier
; #define PG8_STAGE(bufoff, gbase, voff) do { _Pragma("unroll") for (int _i = 0; _i < 2; ++_i) \
;         __builtin_amdgcn_global_load_lds((const unsigned*)((const char*)(gbase) + (voff)[_i]), (PG8_LAS unsigned*)(lds + (bufoff) + ldsw + _i * 8192), 16, 0, 0); } while (0)
; #define PG8_LDA(dst, b, h) do { _Pragma("unroll") for (int m = 0; m < 4; ++m) _Pragma("unroll") for (int k = 0; k < 2; ++k) dst[m][k] = *(const PG8_LAS bf16x8*)(lds + PG8_SA(b, h) + aoff + m * 2048 + k * 1024); } while (0)
; #define PG8_LDB(dst, b, h) do { _Pragma("unroll") for (int n = 0; n < 2; ++n) _Pragma("unroll") for (int k = 0; k < 2; ++k) dst[n][k] = *(const PG8_LAS bf16x8*)(lds + PG8_SB(b, h) + boff + n * 2048 + k * 1024); } while (0)
; #define PG8_MMA(ai, bj, At, Bt) do { __builtin_amdgcn_s_setprio(1); _Pragma("unroll") for (int m = 0; m < 4; ++m) _Pragma("unroll") for (int n = 0; n < 2; ++n) _Pragma("unroll") for (int k = 0; k < 2; ++k) \
;         acc[ai][bj][m][n] = __builtin_amdgcn_mfma_f32_16x16x32_bf16(Bt[n][k], At[m][k], acc[ai][bj][m][n], 0, 0, 0); __builtin_amdgcn_s_setprio(0); } while (0)
; #define PG8_WAIT_V(n) asm volatile("s_waitcnt vmcnt(" #n ")" ::: "memory")
; #define PG8_WAIT_L(n) asm volatile("s_waitcnt lgkmcnt(" #n ")" ::: "memory")
; #define PG8_BAR __builtin_amdgcn_s_barrier()
; #define PG8_SCHED __builtin_amdgcn_sched_barrier(0)
; template <class Epi, class Sched, bool ALIGN_EPI = false, bool SP2 = false>
; __device__ __forceinline__ void gemm_phase(PG8_LAS unsigned char* lds, const Gemm g, const Sched& S, const Epi& E, const int tid_in) {
;     ...
;             PG8_LDA(At, 0, 1); PG8_STAGE(PG8_SB(0, 0), b2, voffB); PG8_STAGE(PG8_SB(0, 1), b2 + hstepB, voffB); PG8_STAGE(PG8_SA(0, 0), a2, voffA);
;             PG8_WAIT_V(8); PG8_WAIT_L(0); PG8_BAR; PG8_MMA(1, 0, At, B0); PG8_MMA(1, 1, At, B1); PG8_BAR; PG8_SCHED;
;             PG8_LDB(B0, 1, 0); PG8_LDB(B1, 1, 1); PG8_SCHED; PG8_LDA(At, 1, 0); PG8_STAGE(PG8_SA(0, 1), a2 + hstepA, voffA);
;             PG8_WAIT_V(8); PG8_WAIT_L(0); PG8_BAR; PG8_MMA(0, 0, At, B0); PG8_MMA(0, 1, At, B1); PG8_BAR; PG8_SCHED;
	s_setprio 1
	s_waitcnt lgkmcnt(0)
	v_mfma_f32_16x16x32_bf16 v[60:63], v[148:151], v[180:183], v[60:63]
	v_mfma_f32_16x16x32_bf16 v[56:59], v[156:159], v[180:183], v[56:59]
	v_mfma_f32_16x16x32_bf16 v[44:47], v[148:151], v[188:191], v[44:47]
	v_mfma_f32_16x16x32_bf16 v[40:43], v[156:159], v[188:191], v[40:43]
	v_mfma_f32_16x16x32_bf16 v[28:31], v[148:151], v[200:203], v[28:31]
	v_mfma_f32_16x16x32_bf16 v[24:27], v[156:159], v[200:203], v[24:27]
	v_mfma_f32_16x16x32_bf16 v[12:15], v[148:151], v[208:211], v[12:15]
	v_mfma_f32_16x16x32_bf16 v[8:11], v[156:159], v[208:211], v[8:11]
	v_mfma_f32_16x16x32_bf16 v[60:63], v[152:155], v[184:187], v[60:63]
	v_mfma_f32_16x16x32_bf16 v[56:59], v[160:163], v[184:187], v[56:59]
	v_mfma_f32_16x16x32_bf16 v[44:47], v[152:155], v[192:195], v[44:47]
	v_mfma_f32_16x16x32_bf16 v[40:43], v[160:163], v[192:195], v[40:43]
	v_mfma_f32_16x16x32_bf16 v[28:31], v[152:155], v[204:207], v[28:31]
	v_mfma_f32_16x16x32_bf16 v[24:27], v[160:163], v[204:207], v[24:27]
	v_mfma_f32_16x16x32_bf16 v[12:15], v[152:155], v[212:215], v[12:15]
	v_mfma_f32_16x16x32_bf16 v[8:11], v[160:163], v[212:215], v[8:11]
	s_setprio 0
	s_setprio 1
	v_mfma_f32_16x16x32_bf16 v[52:55], v[164:167], v[180:183], v[52:55]
	v_mfma_f32_16x16x32_bf16 v[48:51], v[172:175], v[180:183], v[48:51]
	v_mfma_f32_16x16x32_bf16 v[36:39], v[164:167], v[188:191], v[36:39]
	v_mfma_f32_16x16x32_bf16 v[32:35], v[172:175], v[188:191], v[32:35]
	v_mfma_f32_16x16x32_bf16 v[20:23], v[164:167], v[200:203], v[20:23]
	v_mfma_f32_16x16x32_bf16 v[16:19], v[172:175], v[200:203], v[16:19]
	v_mfma_f32_16x16x32_bf16 v[4:7], v[164:167], v[208:211], v[4:7]
	v_mfma_f32_16x16x32_bf16 v[0:3], v[172:175], v[208:211], v[0:3]
	v_mfma_f32_16x16x32_bf16 v[52:55], v[168:171], v[184:187], v[52:55]
	v_mfma_f32_16x16x32_bf16 v[48:51], v[176:179], v[184:187], v[48:51]
	v_mfma_f32_16x16x32_bf16 v[36:39], v[168:171], v[192:195], v[36:39]
	v_mfma_f32_16x16x32_bf16 v[32:35], v[176:179], v[192:195], v[32:35]
	v_mfma_f32_16x16x32_bf16 v[20:23], v[168:171], v[204:207], v[20:23]
	v_mfma_f32_16x16x32_bf16 v[16:19], v[176:179], v[204:207], v[16:19]
	v_mfma_f32_16x16x32_bf16 v[4:7], v[168:171], v[212:215], v[4:7]
	v_mfma_f32_16x16x32_bf16 v[0:3], v[176:179], v[212:215], v[0:3]
	s_setprio 0
	s_barrier
	s_add_i32 s49, 0, 0x18000
	v_add_u32_e32 v142, s49, v143
	s_add_i32 s52, 0, 0x1c000
	ds_read_b128 v[148:151], v142
	ds_read_b128 v[152:155], v142 offset:1024
	ds_read_b128 v[156:159], v142 offset:2048
	ds_read_b128 v[160:163], v142 offset:3072
	v_add_u32_e32 v142, s52, v143
	ds_read_b128 v[164:167], v142
	ds_read_b128 v[168:171], v142 offset:1024
	ds_read_b128 v[172:175], v142 offset:2048
	ds_read_b128 v[176:179], v142 offset:3072
	s_add_u32 s24, s24, 0x40000
	s_addc_u32 s25, s25, 0
	s_mov_b32 m0, s35
	v_lshl_add_u64 v[220:221], s[24:25], 0, v[136:137]
	ds_read_b128 v[180:183], v147 offset:32768
	ds_read_b128 v[184:187], v147 offset:33792
	ds_read_b128 v[188:191], v147 offset:34816
	ds_read_b128 v[192:195], v147 offset:35840
	ds_read_b128 v[200:203], v147 offset:36864
	ds_read_b128 v[204:207], v147 offset:37888
	ds_read_b128 v[208:211], v147 offset:38912
	ds_read_b128 v[212:215], v147 offset:39936
	global_load_lds_dwordx4 v[220:221], off
	v_lshl_add_u64 v[220:221], s[24:25], 0, v[132:133]
	s_mov_b32 m0, s36
	s_nop 0
	global_load_lds_dwordx4 v[220:221], off
	s_waitcnt vmcnt(8)
	s_waitcnt lgkmcnt(0)
	s_barrier
	s_setprio 1
	s_waitcnt lgkmcnt(0)
	v_mfma_f32_16x16x32_bf16 v[128:131], v[148:151], v[180:183], v[128:131]
	v_mfma_f32_16x16x32_bf16 v[124:127], v[156:159], v[180:183], v[124:127]
	v_mfma_f32_16x16x32_bf16 v[112:115], v[148:151], v[188:191], v[112:115]
	v_mfma_f32_16x16x32_bf16 v[108:111], v[156:159], v[188:191], v[108:111]
	v_mfma_f32_16x16x32_bf16 v[92:95], v[148:151], v[200:203], v[92:95]
	v_mfma_f32_16x16x32_bf16 v[88:91], v[156:159], v[200:203], v[88:91]
	v_mfma_f32_16x16x32_bf16 v[76:79], v[148:151], v[208:211], v[76:79]
	v_mfma_f32_16x16x32_bf16 v[72:75], v[156:159], v[208:211], v[72:75]
	v_mfma_f32_16x16x32_bf16 v[128:131], v[152:155], v[184:187], v[128:131]
	v_mfma_f32_16x16x32_bf16 v[124:127], v[160:163], v[184:187], v[124:127]
	v_mfma_f32_16x16x32_bf16 v[112:115], v[152:155], v[192:195], v[112:115]
	v_mfma_f32_16x16x32_bf16 v[108:111], v[160:163], v[192:195], v[108:111]
	v_mfma_f32_16x16x32_bf16 v[92:95], v[152:155], v[204:207], v[92:95]
	v_mfma_f32_16x16x32_bf16 v[88:91], v[160:163], v[204:207], v[88:91]
	v_mfma_f32_16x16x32_bf16 v[76:79], v[152:155], v[212:215], v[76:79]
	v_mfma_f32_16x16x32_bf16 v[72:75], v[160:163], v[212:215], v[72:75]
	s_setprio 0
	s_setprio 1
	v_mfma_f32_16x16x32_bf16 v[120:123], v[164:167], v[180:183], v[120:123]
	v_mfma_f32_16x16x32_bf16 v[116:119], v[172:175], v[180:183], v[116:119]
	v_mfma_f32_16x16x32_bf16 v[104:107], v[164:167], v[188:191], v[104:107]
	v_mfma_f32_16x16x32_bf16 v[100:103], v[172:175], v[188:191], v[100:103]
	v_mfma_f32_16x16x32_bf16 v[84:87], v[164:167], v[200:203], v[84:87]
	v_mfma_f32_16x16x32_bf16 v[80:83], v[172:175], v[200:203], v[80:83]
	v_mfma_f32_16x16x32_bf16 v[68:71], v[164:167], v[208:211], v[68:71]
	v_mfma_f32_16x16x32_bf16 v[64:67], v[172:175], v[208:211], v[64:67]
	v_mfma_f32_16x16x32_bf16 v[120:123], v[168:171], v[184:187], v[120:123]
	v_mfma_f32_16x16x32_bf16 v[116:119], v[176:179], v[184:187], v[116:119]
	v_mfma_f32_16x16x32_bf16 v[104:107], v[168:171], v[192:195], v[104:107]
	v_mfma_f32_16x16x32_bf16 v[100:103], v[176:179], v[192:195], v[100:103]
	v_mfma_f32_16x16x32_bf16 v[84:87], v[168:171], v[204:207], v[84:87]
	v_mfma_f32_16x16x32_bf16 v[80:83], v[176:179], v[204:207], v[80:83]
	v_mfma_f32_16x16x32_bf16 v[68:71], v[168:171], v[212:215], v[68:71]
	v_mfma_f32_16x16x32_bf16 v[64:67], v[176:179], v[212:215], v[64:67]
	s_setprio 0
	s_barrier
; #define PG8_STAGE(bufoff, gbase, voff) do { _Pragma("unroll") for (int _i = 0; _i < 2; ++_i) \
;         __builtin_amdgcn_global_load_lds((const unsigned*)((const char*)(gbase) + (voff)[_i]), (PG8_LAS unsigned*)(lds + (bufoff) + ldsw + _i * 8192), 16, 0, 0); } while (0)
; #define PG8_LDA(dst, b, h) do { _Pragma("unroll") for (int m = 0; m < 4; ++m) _Pragma("unroll") for (int k = 0; k < 2; ++k) dst[m][k] = *(const PG8_LAS bf16x8*)(lds + PG8_SA(b, h) + aoff + m * 2048 + k * 1024); } while (0)
; #define PG8_MMA(ai, bj, At, Bt) do { __builtin_amdgcn_s_setprio(1); _Pragma("unroll") for (int m = 0; m < 4; ++m) _Pragma("unroll") for (int n = 0; n < 2; ++n) _Pragma("unroll") for (int k = 0; k < 2; ++k) \
;         acc[ai][bj][m][n] = __builtin_amdgcn_mfma_f32_16x16x32_bf16(Bt[n][k], At[m][k], acc[ai][bj][m][n], 0, 0, 0); __builtin_amdgcn_s_setprio(0); } while (0)
; #define PG8_WAIT_V(n) asm volatile("s_waitcnt vmcnt(" #n ")" ::: "memory")
; #define PG8_WAIT_L(n) asm volatile("s_waitcnt lgkmcnt(" #n ")" ::: "memory")
; #define PG8_BAR __builtin_amdgcn_s_barrier()
; #define PG8_SCHED __builtin_amdgcn_sched_barrier(0)
; template <class Epi, class Sched, bool ALIGN_EPI = false, bool SP2 = false>
; __device__ __forceinline__ void gemm_phase(PG8_LAS unsigned char* lds, const Gemm g, const Sched& S, const Epi& E, const int tid_in) {
;     ...
;         for (int t = 0; t < nt; t += 2) {
;             const bool last = (t == nt - 2);
;             const char* a1 = cA + (size_t)(t + 1) * kstep;
;             const char* a2 = last ? nA : cA + (size_t)(t + 2) * kstep; const char* b2 = last ? nB : cB + (size_t)(t + 2) * kstep;
;             const char* a3 = a2 + kstep; const char* b3 = b2 + kstep;
;             if (last && has_next) S.a_ready(nxt);
;     ...
;             PG8_LDA(At, 1, 1); PG8_STAGE(PG8_SB(1, 0), b3, voffB); PG8_STAGE(PG8_SB(1, 1), b3 + hstepB, voffB); PG8_STAGE(PG8_SA(1, 0), a3, voffA);
;             PG8_WAIT_V(8); PG8_WAIT_L(0); PG8_BAR; PG8_MMA(1, 0, At, B0); PG8_MMA(1, 1, At, B1); PG8_BAR; PG8_SCHED;
	s_add_i32 s24, s49, s30
	v_lshl_add_u64 v[144:145], v[144:145], 0, s[50:51]
	s_mov_b32 m0, s24
	ds_read_b128 v[180:183], v147 offset:49152
	ds_read_b128 v[184:187], v147 offset:50176
	ds_read_b128 v[188:191], v147 offset:51200
	ds_read_b128 v[192:195], v147 offset:52224
	ds_read_b128 v[200:203], v147 offset:53248
	ds_read_b128 v[204:207], v147 offset:54272
	ds_read_b128 v[208:211], v147 offset:55296
	ds_read_b128 v[212:215], v147 offset:56320
	global_load_lds_dwordx4 v[144:145], off
	s_add_i32 m0, s24, 0x2000
	s_add_u32 s22, s22, 0x40080
	v_lshl_add_u64 v[144:145], v[196:197], 0, s[50:51]
	s_addc_u32 s23, s23, 0
	s_add_i32 s24, s52, s30
	global_load_lds_dwordx4 v[144:145], off
	v_lshl_add_u64 v[144:145], s[22:23], 0, v[134:135]
	s_mov_b32 m0, s24
	s_nop 0
	global_load_lds_dwordx4 v[144:145], off
	v_lshl_add_u64 v[144:145], s[22:23], 0, v[96:97]
	s_add_i32 m0, s24, 0x2000
	s_nop 0
	global_load_lds_dwordx4 v[144:145], off
	v_lshl_add_u64 v[144:145], v[216:217], 0, s[50:51]
	s_mov_b32 m0, s39
	s_nop 0
	global_load_lds_dwordx4 v[144:145], off
	v_lshl_add_u64 v[144:145], v[218:219], 0, s[50:51]
	s_mov_b32 m0, s40
	s_nop 0
	global_load_lds_dwordx4 v[144:145], off
	s_waitcnt vmcnt(8)
	s_waitcnt lgkmcnt(0)
	s_barrier
	s_setprio 1
	s_waitcnt lgkmcnt(0)
	v_mfma_f32_16x16x32_bf16 v[60:63], v[148:151], v[180:183], v[60:63]
	v_mfma_f32_16x16x32_bf16 v[56:59], v[156:159], v[180:183], v[56:59]
	v_mfma_f32_16x16x32_bf16 v[44:47], v[148:151], v[188:191], v[44:47]
	v_mfma_f32_16x16x32_bf16 v[40:43], v[156:159], v[188:191], v[40:43]
	v_mfma_f32_16x16x32_bf16 v[28:31], v[148:151], v[200:203], v[28:31]
	v_mfma_f32_16x16x32_bf16 v[24:27], v[156:159], v[200:203], v[24:27]
	v_mfma_f32_16x16x32_bf16 v[12:15], v[148:151], v[208:211], v[12:15]
	v_mfma_f32_16x16x32_bf16 v[8:11], v[156:159], v[208:211], v[8:11]
	v_mfma_f32_16x16x32_bf16 v[60:63], v[152:155], v[184:187], v[60:63]
	v_mfma_f32_16x16x32_bf16 v[56:59], v[160:163], v[184:187], v[56:59]
	v_mfma_f32_16x16x32_bf16 v[44:47], v[152:155], v[192:195], v[44:47]
	v_mfma_f32_16x16x32_bf16 v[40:43], v[160:163], v[192:195], v[40:43]
	v_mfma_f32_16x16x32_bf16 v[28:31], v[152:155], v[204:207], v[28:31]
	v_mfma_f32_16x16x32_bf16 v[24:27], v[160:163], v[204:207], v[24:27]
	v_mfma_f32_16x16x32_bf16 v[12:15], v[152:155], v[212:215], v[12:15]
	v_mfma_f32_16x16x32_bf16 v[8:11], v[160:163], v[212:215], v[8:11]
	s_setprio 0
	s_setprio 1
	v_mfma_f32_16x16x32_bf16 v[52:55], v[164:167], v[180:183], v[52:55]
	v_mfma_f32_16x16x32_bf16 v[48:51], v[172:175], v[180:183], v[48:51]
	v_mfma_f32_16x16x32_bf16 v[36:39], v[164:167], v[188:191], v[36:39]
	v_mfma_f32_16x16x32_bf16 v[32:35], v[172:175], v[188:191], v[32:35]
	v_mfma_f32_16x16x32_bf16 v[20:23], v[164:167], v[200:203], v[20:23]
	v_mfma_f32_16x16x32_bf16 v[16:19], v[172:175], v[200:203], v[16:19]
	v_mfma_f32_16x16x32_bf16 v[4:7], v[164:167], v[208:211], v[4:7]
	v_mfma_f32_16x16x32_bf16 v[0:3], v[172:175], v[208:211], v[0:3]
	v_mfma_f32_16x16x32_bf16 v[52:55], v[168:171], v[184:187], v[52:55]
	v_mfma_f32_16x16x32_bf16 v[48:51], v[176:179], v[184:187], v[48:51]
	v_mfma_f32_16x16x32_bf16 v[36:39], v[168:171], v[192:195], v[36:39]
	v_mfma_f32_16x16x32_bf16 v[32:35], v[176:179], v[192:195], v[32:35]
	v_mfma_f32_16x16x32_bf16 v[20:23], v[168:171], v[204:207], v[20:23]
	v_mfma_f32_16x16x32_bf16 v[16:19], v[176:179], v[204:207], v[16:19]
	v_mfma_f32_16x16x32_bf16 v[4:7], v[168:171], v[212:215], v[4:7]
	v_mfma_f32_16x16x32_bf16 v[0:3], v[176:179], v[212:215], v[0:3]
	s_add_i32 s48, s48, 2
	s_add_u32 s20, s20, 0x100
	s_addc_u32 s21, s21, 0
	s_add_u32 s46, s46, 0x100
	s_addc_u32 s47, s47, 0
	s_cmp_gt_u32 s48, 13
	s_setprio 0
	s_barrier
	s_cbranch_scc0 .LBB0_1131
	s_and_b64 vcc, exec, s[10:11]
	s_cbranch_vccz .LBB0_1134
	s_barrier
